# ph3: all 64 row loads of a wave issued up front (memory-level parallelism x8), counted waits per row
# speedup vs baseline: 1.0026x; 1.0026x over previous
.LBB0_417:
	s_andn2_b64 vcc, exec, s[10:11]
	s_cbranch_vccnz .LBB0_441
	s_cmp_lg_u32 s87, 3
	s_cbranch_scc1 .LBB0_441
	v_mov_b32_e32 v1, v163
	s_mov_b32 s2, s75
	v_ashrrev_i32_e32 v2, 6, v1
	s_nop 0
	v_lshl_add_u32 v6, s2, 3, v2
	v_cmp_gt_i32_e32 vcc, s83, v6
	s_and_saveexec_b64 s[10:11], vcc
	s_cbranch_execz .LBB0_440
	v_and_b32_e32 v1, 63, v1
	v_lshlrev_b32_e32 v2, 3, v1
	v_mov_b32_e32 v3, v0
	v_lshl_add_u64 v[10:11], s[66:67], 0, v[2:3]
	s_mov_b64 s[2:3], 0x18000000
	v_lshl_add_u64 v[8:9], v[10:11], 0, s[2:3]
	s_load_dwordx2 s[2:3], s[0:1], 0x30
	v_lshlrev_b32_e32 v2, 4, v1
	v_cmp_gt_u32_e64 s[40:41], 32, v1
	s_mov_b64 s[12:13], 0
	s_waitcnt lgkmcnt(0)
	v_lshl_add_u64 v[2:3], s[2:3], 0, v[2:3]
	v_add_co_u32_e32 v2, vcc, 0x1000, v2
	s_mov_b64 s[2:3], 0xa000000
	s_nop 0
	v_addc_co_u32_e32 v3, vcc, 0, v3, vcc
	global_load_dwordx4 v[2:5], v[2:3], off offset:2048
	v_cmp_lt_u32_e32 vcc, 15, v1
	v_lshl_add_u64 v[10:11], v[10:11], 0, s[2:3]
	s_and_b64 s[42:43], vcc, s[40:41]
	v_mov_b32_e32 v12, 0x4038aa3b
	v_mov_b32_e32 v13, 0xbfb8aa3b
	v_cndmask_b32_e32 v12, v12, v13, vcc
	v_mov_b32_e32 v13, -2.0
	v_mov_b32_e32 v14, 1.0
	v_cndmask_b32_e32 v13, v13, v14, vcc
	v_mov_b32_e32 v15, 0
	v_cndmask_b32_e32 v14, v14, v15, vcc
	s_movk_i32 s2, 0xe00
	v_mov_b32_e32 v224, v6
	v_mad_i64_i32 v[208:209], s[14:15], v224, s2, v[10:11]
	global_load_dwordx2 v[16:17], v[208:209], off offset:3072
	global_load_dwordx2 v[48:49], v[208:209], off offset:-512
	v_add_u32_e32 v224, s33, v224
	v_mad_i64_i32 v[208:209], s[14:15], v224, s2, v[10:11]
	global_load_dwordx2 v[18:19], v[208:209], off offset:3072
	global_load_dwordx2 v[50:51], v[208:209], off offset:-512
	v_add_u32_e32 v224, s33, v224
	v_mad_i64_i32 v[208:209], s[14:15], v224, s2, v[10:11]
	global_load_dwordx2 v[20:21], v[208:209], off offset:3072
	global_load_dwordx2 v[52:53], v[208:209], off offset:-512
	v_add_u32_e32 v224, s33, v224
	v_mad_i64_i32 v[208:209], s[14:15], v224, s2, v[10:11]
	global_load_dwordx2 v[22:23], v[208:209], off offset:3072
	global_load_dwordx2 v[54:55], v[208:209], off offset:-512
	v_add_u32_e32 v224, s33, v224
	v_mad_i64_i32 v[208:209], s[14:15], v224, s2, v[10:11]
	global_load_dwordx2 v[24:25], v[208:209], off offset:3072
	global_load_dwordx2 v[56:57], v[208:209], off offset:-512
	v_add_u32_e32 v224, s33, v224
	v_mad_i64_i32 v[208:209], s[14:15], v224, s2, v[10:11]
	global_load_dwordx2 v[26:27], v[208:209], off offset:3072
	global_load_dwordx2 v[58:59], v[208:209], off offset:-512
	v_add_u32_e32 v224, s33, v224
	v_mad_i64_i32 v[208:209], s[14:15], v224, s2, v[10:11]
	global_load_dwordx2 v[28:29], v[208:209], off offset:3072
	global_load_dwordx2 v[60:61], v[208:209], off offset:-512
	v_add_u32_e32 v224, s33, v224
	v_mad_i64_i32 v[208:209], s[14:15], v224, s2, v[10:11]
	global_load_dwordx2 v[30:31], v[208:209], off offset:3072
	global_load_dwordx2 v[62:63], v[208:209], off offset:-512
	v_add_u32_e32 v224, s33, v224
	v_mad_i64_i32 v[208:209], s[14:15], v224, s2, v[10:11]
	global_load_dwordx2 v[32:33], v[208:209], off offset:3072
	global_load_dwordx2 v[64:65], v[208:209], off offset:-512
	v_add_u32_e32 v224, s33, v224
	v_mad_i64_i32 v[208:209], s[14:15], v224, s2, v[10:11]
	global_load_dwordx2 v[34:35], v[208:209], off offset:3072
	global_load_dwordx2 v[66:67], v[208:209], off offset:-512
	v_add_u32_e32 v224, s33, v224
	v_mad_i64_i32 v[208:209], s[14:15], v224, s2, v[10:11]
	global_load_dwordx2 v[36:37], v[208:209], off offset:3072
	global_load_dwordx2 v[68:69], v[208:209], off offset:-512
	v_add_u32_e32 v224, s33, v224
	v_mad_i64_i32 v[208:209], s[14:15], v224, s2, v[10:11]
	global_load_dwordx2 v[38:39], v[208:209], off offset:3072
	global_load_dwordx2 v[70:71], v[208:209], off offset:-512
	v_add_u32_e32 v224, s33, v224
	v_mad_i64_i32 v[208:209], s[14:15], v224, s2, v[10:11]
	global_load_dwordx2 v[40:41], v[208:209], off offset:3072
	global_load_dwordx2 v[72:73], v[208:209], off offset:-512
	v_add_u32_e32 v224, s33, v224
	v_mad_i64_i32 v[208:209], s[14:15], v224, s2, v[10:11]
	global_load_dwordx2 v[42:43], v[208:209], off offset:3072
	global_load_dwordx2 v[74:75], v[208:209], off offset:-512
	v_add_u32_e32 v224, s33, v224
	v_mad_i64_i32 v[208:209], s[14:15], v224, s2, v[10:11]
	global_load_dwordx2 v[44:45], v[208:209], off offset:3072
	global_load_dwordx2 v[76:77], v[208:209], off offset:-512
	v_add_u32_e32 v224, s33, v224
	v_mad_i64_i32 v[208:209], s[14:15], v224, s2, v[10:11]
	global_load_dwordx2 v[46:47], v[208:209], off offset:3072
	global_load_dwordx2 v[78:79], v[208:209], off offset:-512
	v_add_u32_e32 v224, s33, v224
	v_mad_i64_i32 v[208:209], s[14:15], v224, s2, v[10:11]
	global_load_dwordx2 v[80:81], v[208:209], off offset:3072
	global_load_dwordx2 v[112:113], v[208:209], off offset:-512
	v_add_u32_e32 v224, s33, v224
	v_mad_i64_i32 v[208:209], s[14:15], v224, s2, v[10:11]
	global_load_dwordx2 v[82:83], v[208:209], off offset:3072
	global_load_dwordx2 v[114:115], v[208:209], off offset:-512
	v_add_u32_e32 v224, s33, v224
	v_mad_i64_i32 v[208:209], s[14:15], v224, s2, v[10:11]
	global_load_dwordx2 v[84:85], v[208:209], off offset:3072
	global_load_dwordx2 v[116:117], v[208:209], off offset:-512
	v_add_u32_e32 v224, s33, v224
	v_mad_i64_i32 v[208:209], s[14:15], v224, s2, v[10:11]
	global_load_dwordx2 v[86:87], v[208:209], off offset:3072
	global_load_dwordx2 v[118:119], v[208:209], off offset:-512
	v_add_u32_e32 v224, s33, v224
	v_mad_i64_i32 v[208:209], s[14:15], v224, s2, v[10:11]
	global_load_dwordx2 v[88:89], v[208:209], off offset:3072
	global_load_dwordx2 v[120:121], v[208:209], off offset:-512
	v_add_u32_e32 v224, s33, v224
	v_mad_i64_i32 v[208:209], s[14:15], v224, s2, v[10:11]
	global_load_dwordx2 v[90:91], v[208:209], off offset:3072
	global_load_dwordx2 v[122:123], v[208:209], off offset:-512
	v_add_u32_e32 v224, s33, v224
	v_mad_i64_i32 v[208:209], s[14:15], v224, s2, v[10:11]
	global_load_dwordx2 v[92:93], v[208:209], off offset:3072
	global_load_dwordx2 v[124:125], v[208:209], off offset:-512
	v_add_u32_e32 v224, s33, v224
	v_mad_i64_i32 v[208:209], s[14:15], v224, s2, v[10:11]
	global_load_dwordx2 v[94:95], v[208:209], off offset:3072
	global_load_dwordx2 v[126:127], v[208:209], off offset:-512
	v_add_u32_e32 v224, s33, v224
	v_mad_i64_i32 v[208:209], s[14:15], v224, s2, v[10:11]
	global_load_dwordx2 v[96:97], v[208:209], off offset:3072
	global_load_dwordx2 v[128:129], v[208:209], off offset:-512
	v_add_u32_e32 v224, s33, v224
	v_mad_i64_i32 v[208:209], s[14:15], v224, s2, v[10:11]
	global_load_dwordx2 v[98:99], v[208:209], off offset:3072
	global_load_dwordx2 v[130:131], v[208:209], off offset:-512
	v_add_u32_e32 v224, s33, v224
	v_mad_i64_i32 v[208:209], s[14:15], v224, s2, v[10:11]
	global_load_dwordx2 v[100:101], v[208:209], off offset:3072
	global_load_dwordx2 v[132:133], v[208:209], off offset:-512
	v_add_u32_e32 v224, s33, v224
	v_mad_i64_i32 v[208:209], s[14:15], v224, s2, v[10:11]
	global_load_dwordx2 v[102:103], v[208:209], off offset:3072
	global_load_dwordx2 v[134:135], v[208:209], off offset:-512
	v_add_u32_e32 v224, s33, v224
	v_mad_i64_i32 v[208:209], s[14:15], v224, s2, v[10:11]
	global_load_dwordx2 v[104:105], v[208:209], off offset:3072
	global_load_dwordx2 v[136:137], v[208:209], off offset:-512
	v_add_u32_e32 v224, s33, v224
	v_mad_i64_i32 v[208:209], s[14:15], v224, s2, v[10:11]
	global_load_dwordx2 v[106:107], v[208:209], off offset:3072
	global_load_dwordx2 v[138:139], v[208:209], off offset:-512
	v_add_u32_e32 v224, s33, v224
	v_mad_i64_i32 v[208:209], s[14:15], v224, s2, v[10:11]
	global_load_dwordx2 v[108:109], v[208:209], off offset:3072
	global_load_dwordx2 v[140:141], v[208:209], off offset:-512
	v_add_u32_e32 v224, s33, v224
	v_mad_i64_i32 v[208:209], s[14:15], v224, s2, v[10:11]
	global_load_dwordx2 v[110:111], v[208:209], off offset:3072
	global_load_dwordx2 v[142:143], v[208:209], off offset:-512
	v_mov_b32_e32 v224, v6
	s_waitcnt vmcnt(62)
	v_and_b32_e32 v210, 0x7ff, v224
	v_cmp_ne_u32_e32 vcc, 0, v210
	v_lshlrev_b32_e32 v212, 16, v16
	v_and_b32_e32 v213, 0xffff0000, v16
	v_lshlrev_b32_e32 v214, 16, v17
	v_and_b32_e32 v215, 0xffff0000, v17
	v_cndmask_b32_e32 v48, 0, v48, vcc
	v_cndmask_b32_e32 v49, 0, v49, vcc
	v_lshlrev_b32_e32 v216, 16, v48
	v_and_b32_e32 v217, 0xffff0000, v48
	v_lshlrev_b32_e32 v218, 16, v49
	v_and_b32_e32 v219, 0xffff0000, v49
	v_sub_f32_e32 v216, v216, v212
	v_sub_f32_e32 v217, v217, v213
	v_sub_f32_e32 v218, v218, v214
	v_sub_f32_e32 v219, v219, v215
	v_fmac_f32_e32 v212, v2, v216
	v_fmac_f32_e32 v213, v3, v217
	v_fmac_f32_e32 v214, v4, v218
	v_fmac_f32_e32 v215, v5, v219
	v_mul_f32_e32 v216, v12, v212
	v_mul_f32_e32 v217, v12, v213
	v_mul_f32_e32 v218, v12, v214
	v_mul_f32_e32 v219, v12, v215
	v_exp_f32_e32 v216, v216
	v_exp_f32_e32 v217, v217
	v_exp_f32_e32 v218, v218
	v_exp_f32_e32 v219, v219
	v_add_f32_e32 v216, 1.0, v216
	v_add_f32_e32 v217, 1.0, v217
	v_add_f32_e32 v218, 1.0, v218
	v_add_f32_e32 v219, 1.0, v219
	v_rcp_f32_e32 v216, v216
	v_rcp_f32_e32 v217, v217
	v_rcp_f32_e32 v218, v218
	v_rcp_f32_e32 v219, v219
	v_fma_f32 v216, v216, v13, v14
	v_fma_f32 v217, v217, v13, v14
	v_fma_f32 v218, v218, v13, v14
	v_fma_f32 v219, v219, v13, v14
	v_cndmask_b32_e64 v216, v216, v212, s[42:43]
	v_cndmask_b32_e64 v217, v217, v213, s[42:43]
	v_cndmask_b32_e64 v218, v218, v214, s[42:43]
	v_cndmask_b32_e64 v219, v219, v215, s[42:43]
	v_cvt_pk_bf16_f32 v220, v216, v217
	v_cvt_pk_bf16_f32 v221, v218, v219
	v_ashrrev_i32_e32 v225, 31, v224
	v_lshlrev_b64 v[222:223], 9, v[224:225]
	v_lshl_add_u64 v[222:223], v[8:9], 0, v[222:223]
	global_store_dwordx2 v[222:223], v[220:221], off
	s_waitcnt vmcnt(61)
	v_add_u32_e32 v224, s33, v224
	v_and_b32_e32 v210, 0x7ff, v224
	v_cmp_ne_u32_e32 vcc, 0, v210
	v_lshlrev_b32_e32 v212, 16, v18
	v_and_b32_e32 v213, 0xffff0000, v18
	v_lshlrev_b32_e32 v214, 16, v19
	v_and_b32_e32 v215, 0xffff0000, v19
	v_cndmask_b32_e32 v50, 0, v50, vcc
	v_cndmask_b32_e32 v51, 0, v51, vcc
	v_lshlrev_b32_e32 v216, 16, v50
	v_and_b32_e32 v217, 0xffff0000, v50
	v_lshlrev_b32_e32 v218, 16, v51
	v_and_b32_e32 v219, 0xffff0000, v51
	v_sub_f32_e32 v216, v216, v212
	v_sub_f32_e32 v217, v217, v213
	v_sub_f32_e32 v218, v218, v214
	v_sub_f32_e32 v219, v219, v215
	v_fmac_f32_e32 v212, v2, v216
	v_fmac_f32_e32 v213, v3, v217
	v_fmac_f32_e32 v214, v4, v218
	v_fmac_f32_e32 v215, v5, v219
	v_mul_f32_e32 v216, v12, v212
	v_mul_f32_e32 v217, v12, v213
	v_mul_f32_e32 v218, v12, v214
	v_mul_f32_e32 v219, v12, v215
	v_exp_f32_e32 v216, v216
	v_exp_f32_e32 v217, v217
	v_exp_f32_e32 v218, v218
	v_exp_f32_e32 v219, v219
	v_add_f32_e32 v216, 1.0, v216
	v_add_f32_e32 v217, 1.0, v217
	v_add_f32_e32 v218, 1.0, v218
	v_add_f32_e32 v219, 1.0, v219
	v_rcp_f32_e32 v216, v216
	v_rcp_f32_e32 v217, v217
	v_rcp_f32_e32 v218, v218
	v_rcp_f32_e32 v219, v219
	v_fma_f32 v216, v216, v13, v14
	v_fma_f32 v217, v217, v13, v14
	v_fma_f32 v218, v218, v13, v14
	v_fma_f32 v219, v219, v13, v14
	v_cndmask_b32_e64 v216, v216, v212, s[42:43]
	v_cndmask_b32_e64 v217, v217, v213, s[42:43]
	v_cndmask_b32_e64 v218, v218, v214, s[42:43]
	v_cndmask_b32_e64 v219, v219, v215, s[42:43]
	v_cvt_pk_bf16_f32 v226, v216, v217
	v_cvt_pk_bf16_f32 v227, v218, v219
	v_ashrrev_i32_e32 v225, 31, v224
	v_lshlrev_b64 v[222:223], 9, v[224:225]
	v_lshl_add_u64 v[222:223], v[8:9], 0, v[222:223]
	global_store_dwordx2 v[222:223], v[226:227], off
	s_waitcnt vmcnt(60)
	v_add_u32_e32 v224, s33, v224
	v_and_b32_e32 v210, 0x7ff, v224
	v_cmp_ne_u32_e32 vcc, 0, v210
	v_lshlrev_b32_e32 v212, 16, v20
	v_and_b32_e32 v213, 0xffff0000, v20
	v_lshlrev_b32_e32 v214, 16, v21
	v_and_b32_e32 v215, 0xffff0000, v21
	v_cndmask_b32_e32 v52, 0, v52, vcc
	v_cndmask_b32_e32 v53, 0, v53, vcc
	v_lshlrev_b32_e32 v216, 16, v52
	v_and_b32_e32 v217, 0xffff0000, v52
	v_lshlrev_b32_e32 v218, 16, v53
	v_and_b32_e32 v219, 0xffff0000, v53
	v_sub_f32_e32 v216, v216, v212
	v_sub_f32_e32 v217, v217, v213
	v_sub_f32_e32 v218, v218, v214
	v_sub_f32_e32 v219, v219, v215
	v_fmac_f32_e32 v212, v2, v216
	v_fmac_f32_e32 v213, v3, v217
	v_fmac_f32_e32 v214, v4, v218
	v_fmac_f32_e32 v215, v5, v219
	v_mul_f32_e32 v216, v12, v212
	v_mul_f32_e32 v217, v12, v213
	v_mul_f32_e32 v218, v12, v214
	v_mul_f32_e32 v219, v12, v215
	v_exp_f32_e32 v216, v216
	v_exp_f32_e32 v217, v217
	v_exp_f32_e32 v218, v218
	v_exp_f32_e32 v219, v219
	v_add_f32_e32 v216, 1.0, v216
	v_add_f32_e32 v217, 1.0, v217
	v_add_f32_e32 v218, 1.0, v218
	v_add_f32_e32 v219, 1.0, v219
	v_rcp_f32_e32 v216, v216
	v_rcp_f32_e32 v217, v217
	v_rcp_f32_e32 v218, v218
	v_rcp_f32_e32 v219, v219
	v_fma_f32 v216, v216, v13, v14
	v_fma_f32 v217, v217, v13, v14
	v_fma_f32 v218, v218, v13, v14
	v_fma_f32 v219, v219, v13, v14
	v_cndmask_b32_e64 v216, v216, v212, s[42:43]
	v_cndmask_b32_e64 v217, v217, v213, s[42:43]
	v_cndmask_b32_e64 v218, v218, v214, s[42:43]
	v_cndmask_b32_e64 v219, v219, v215, s[42:43]
	v_cvt_pk_bf16_f32 v220, v216, v217
	v_cvt_pk_bf16_f32 v221, v218, v219
	v_ashrrev_i32_e32 v225, 31, v224
	v_lshlrev_b64 v[222:223], 9, v[224:225]
	v_lshl_add_u64 v[222:223], v[8:9], 0, v[222:223]
	global_store_dwordx2 v[222:223], v[220:221], off
	s_waitcnt vmcnt(59)
	v_add_u32_e32 v224, s33, v224
	v_and_b32_e32 v210, 0x7ff, v224
	v_cmp_ne_u32_e32 vcc, 0, v210
	v_lshlrev_b32_e32 v212, 16, v22
	v_and_b32_e32 v213, 0xffff0000, v22
	v_lshlrev_b32_e32 v214, 16, v23
	v_and_b32_e32 v215, 0xffff0000, v23
	v_cndmask_b32_e32 v54, 0, v54, vcc
	v_cndmask_b32_e32 v55, 0, v55, vcc
	v_lshlrev_b32_e32 v216, 16, v54
	v_and_b32_e32 v217, 0xffff0000, v54
	v_lshlrev_b32_e32 v218, 16, v55
	v_and_b32_e32 v219, 0xffff0000, v55
	v_sub_f32_e32 v216, v216, v212
	v_sub_f32_e32 v217, v217, v213
	v_sub_f32_e32 v218, v218, v214
	v_sub_f32_e32 v219, v219, v215
	v_fmac_f32_e32 v212, v2, v216
	v_fmac_f32_e32 v213, v3, v217
	v_fmac_f32_e32 v214, v4, v218
	v_fmac_f32_e32 v215, v5, v219
	v_mul_f32_e32 v216, v12, v212
	v_mul_f32_e32 v217, v12, v213
	v_mul_f32_e32 v218, v12, v214
	v_mul_f32_e32 v219, v12, v215
	v_exp_f32_e32 v216, v216
	v_exp_f32_e32 v217, v217
	v_exp_f32_e32 v218, v218
	v_exp_f32_e32 v219, v219
	v_add_f32_e32 v216, 1.0, v216
	v_add_f32_e32 v217, 1.0, v217
	v_add_f32_e32 v218, 1.0, v218
	v_add_f32_e32 v219, 1.0, v219
	v_rcp_f32_e32 v216, v216
	v_rcp_f32_e32 v217, v217
	v_rcp_f32_e32 v218, v218
	v_rcp_f32_e32 v219, v219
	v_fma_f32 v216, v216, v13, v14
	v_fma_f32 v217, v217, v13, v14
	v_fma_f32 v218, v218, v13, v14
	v_fma_f32 v219, v219, v13, v14
	v_cndmask_b32_e64 v216, v216, v212, s[42:43]
	v_cndmask_b32_e64 v217, v217, v213, s[42:43]
	v_cndmask_b32_e64 v218, v218, v214, s[42:43]
	v_cndmask_b32_e64 v219, v219, v215, s[42:43]
	v_cvt_pk_bf16_f32 v226, v216, v217
	v_cvt_pk_bf16_f32 v227, v218, v219
	v_ashrrev_i32_e32 v225, 31, v224
	v_lshlrev_b64 v[222:223], 9, v[224:225]
	v_lshl_add_u64 v[222:223], v[8:9], 0, v[222:223]
	global_store_dwordx2 v[222:223], v[226:227], off
	s_waitcnt vmcnt(58)
	v_add_u32_e32 v224, s33, v224
	v_and_b32_e32 v210, 0x7ff, v224
	v_cmp_ne_u32_e32 vcc, 0, v210
	v_lshlrev_b32_e32 v212, 16, v24
	v_and_b32_e32 v213, 0xffff0000, v24
	v_lshlrev_b32_e32 v214, 16, v25
	v_and_b32_e32 v215, 0xffff0000, v25
	v_cndmask_b32_e32 v56, 0, v56, vcc
	v_cndmask_b32_e32 v57, 0, v57, vcc
	v_lshlrev_b32_e32 v216, 16, v56
	v_and_b32_e32 v217, 0xffff0000, v56
	v_lshlrev_b32_e32 v218, 16, v57
	v_and_b32_e32 v219, 0xffff0000, v57
	v_sub_f32_e32 v216, v216, v212
	v_sub_f32_e32 v217, v217, v213
	v_sub_f32_e32 v218, v218, v214
	v_sub_f32_e32 v219, v219, v215
	v_fmac_f32_e32 v212, v2, v216
	v_fmac_f32_e32 v213, v3, v217
	v_fmac_f32_e32 v214, v4, v218
	v_fmac_f32_e32 v215, v5, v219
	v_mul_f32_e32 v216, v12, v212
	v_mul_f32_e32 v217, v12, v213
	v_mul_f32_e32 v218, v12, v214
	v_mul_f32_e32 v219, v12, v215
	v_exp_f32_e32 v216, v216
	v_exp_f32_e32 v217, v217
	v_exp_f32_e32 v218, v218
	v_exp_f32_e32 v219, v219
	v_add_f32_e32 v216, 1.0, v216
	v_add_f32_e32 v217, 1.0, v217
	v_add_f32_e32 v218, 1.0, v218
	v_add_f32_e32 v219, 1.0, v219
	v_rcp_f32_e32 v216, v216
	v_rcp_f32_e32 v217, v217
	v_rcp_f32_e32 v218, v218
	v_rcp_f32_e32 v219, v219
	v_fma_f32 v216, v216, v13, v14
	v_fma_f32 v217, v217, v13, v14
	v_fma_f32 v218, v218, v13, v14
	v_fma_f32 v219, v219, v13, v14
	v_cndmask_b32_e64 v216, v216, v212, s[42:43]
	v_cndmask_b32_e64 v217, v217, v213, s[42:43]
	v_cndmask_b32_e64 v218, v218, v214, s[42:43]
	v_cndmask_b32_e64 v219, v219, v215, s[42:43]
	v_cvt_pk_bf16_f32 v220, v216, v217
	v_cvt_pk_bf16_f32 v221, v218, v219
	v_ashrrev_i32_e32 v225, 31, v224
	v_lshlrev_b64 v[222:223], 9, v[224:225]
	v_lshl_add_u64 v[222:223], v[8:9], 0, v[222:223]
	global_store_dwordx2 v[222:223], v[220:221], off
	s_waitcnt vmcnt(57)
	v_add_u32_e32 v224, s33, v224
	v_and_b32_e32 v210, 0x7ff, v224
	v_cmp_ne_u32_e32 vcc, 0, v210
	v_lshlrev_b32_e32 v212, 16, v26
	v_and_b32_e32 v213, 0xffff0000, v26
	v_lshlrev_b32_e32 v214, 16, v27
	v_and_b32_e32 v215, 0xffff0000, v27
	v_cndmask_b32_e32 v58, 0, v58, vcc
	v_cndmask_b32_e32 v59, 0, v59, vcc
	v_lshlrev_b32_e32 v216, 16, v58
	v_and_b32_e32 v217, 0xffff0000, v58
	v_lshlrev_b32_e32 v218, 16, v59
	v_and_b32_e32 v219, 0xffff0000, v59
	v_sub_f32_e32 v216, v216, v212
	v_sub_f32_e32 v217, v217, v213
	v_sub_f32_e32 v218, v218, v214
	v_sub_f32_e32 v219, v219, v215
	v_fmac_f32_e32 v212, v2, v216
	v_fmac_f32_e32 v213, v3, v217
	v_fmac_f32_e32 v214, v4, v218
	v_fmac_f32_e32 v215, v5, v219
	v_mul_f32_e32 v216, v12, v212
	v_mul_f32_e32 v217, v12, v213
	v_mul_f32_e32 v218, v12, v214
	v_mul_f32_e32 v219, v12, v215
	v_exp_f32_e32 v216, v216
	v_exp_f32_e32 v217, v217
	v_exp_f32_e32 v218, v218
	v_exp_f32_e32 v219, v219
	v_add_f32_e32 v216, 1.0, v216
	v_add_f32_e32 v217, 1.0, v217
	v_add_f32_e32 v218, 1.0, v218
	v_add_f32_e32 v219, 1.0, v219
	v_rcp_f32_e32 v216, v216
	v_rcp_f32_e32 v217, v217
	v_rcp_f32_e32 v218, v218
	v_rcp_f32_e32 v219, v219
	v_fma_f32 v216, v216, v13, v14
	v_fma_f32 v217, v217, v13, v14
	v_fma_f32 v218, v218, v13, v14
	v_fma_f32 v219, v219, v13, v14
	v_cndmask_b32_e64 v216, v216, v212, s[42:43]
	v_cndmask_b32_e64 v217, v217, v213, s[42:43]
	v_cndmask_b32_e64 v218, v218, v214, s[42:43]
	v_cndmask_b32_e64 v219, v219, v215, s[42:43]
	v_cvt_pk_bf16_f32 v226, v216, v217
	v_cvt_pk_bf16_f32 v227, v218, v219
	v_ashrrev_i32_e32 v225, 31, v224
	v_lshlrev_b64 v[222:223], 9, v[224:225]
	v_lshl_add_u64 v[222:223], v[8:9], 0, v[222:223]
	global_store_dwordx2 v[222:223], v[226:227], off
	s_waitcnt vmcnt(56)
	v_add_u32_e32 v224, s33, v224
	v_and_b32_e32 v210, 0x7ff, v224
	v_cmp_ne_u32_e32 vcc, 0, v210
	v_lshlrev_b32_e32 v212, 16, v28
	v_and_b32_e32 v213, 0xffff0000, v28
	v_lshlrev_b32_e32 v214, 16, v29
	v_and_b32_e32 v215, 0xffff0000, v29
	v_cndmask_b32_e32 v60, 0, v60, vcc
	v_cndmask_b32_e32 v61, 0, v61, vcc
	v_lshlrev_b32_e32 v216, 16, v60
	v_and_b32_e32 v217, 0xffff0000, v60
	v_lshlrev_b32_e32 v218, 16, v61
	v_and_b32_e32 v219, 0xffff0000, v61
	v_sub_f32_e32 v216, v216, v212
	v_sub_f32_e32 v217, v217, v213
	v_sub_f32_e32 v218, v218, v214
	v_sub_f32_e32 v219, v219, v215
	v_fmac_f32_e32 v212, v2, v216
	v_fmac_f32_e32 v213, v3, v217
	v_fmac_f32_e32 v214, v4, v218
	v_fmac_f32_e32 v215, v5, v219
	v_mul_f32_e32 v216, v12, v212
	v_mul_f32_e32 v217, v12, v213
	v_mul_f32_e32 v218, v12, v214
	v_mul_f32_e32 v219, v12, v215
	v_exp_f32_e32 v216, v216
	v_exp_f32_e32 v217, v217
	v_exp_f32_e32 v218, v218
	v_exp_f32_e32 v219, v219
	v_add_f32_e32 v216, 1.0, v216
	v_add_f32_e32 v217, 1.0, v217
	v_add_f32_e32 v218, 1.0, v218
	v_add_f32_e32 v219, 1.0, v219
	v_rcp_f32_e32 v216, v216
	v_rcp_f32_e32 v217, v217
	v_rcp_f32_e32 v218, v218
	v_rcp_f32_e32 v219, v219
	v_fma_f32 v216, v216, v13, v14
	v_fma_f32 v217, v217, v13, v14
	v_fma_f32 v218, v218, v13, v14
	v_fma_f32 v219, v219, v13, v14
	v_cndmask_b32_e64 v216, v216, v212, s[42:43]
	v_cndmask_b32_e64 v217, v217, v213, s[42:43]
	v_cndmask_b32_e64 v218, v218, v214, s[42:43]
	v_cndmask_b32_e64 v219, v219, v215, s[42:43]
	v_cvt_pk_bf16_f32 v220, v216, v217
	v_cvt_pk_bf16_f32 v221, v218, v219
	v_ashrrev_i32_e32 v225, 31, v224
	v_lshlrev_b64 v[222:223], 9, v[224:225]
	v_lshl_add_u64 v[222:223], v[8:9], 0, v[222:223]
	global_store_dwordx2 v[222:223], v[220:221], off
	s_waitcnt vmcnt(55)
	v_add_u32_e32 v224, s33, v224
	v_and_b32_e32 v210, 0x7ff, v224
	v_cmp_ne_u32_e32 vcc, 0, v210
	v_lshlrev_b32_e32 v212, 16, v30
	v_and_b32_e32 v213, 0xffff0000, v30
	v_lshlrev_b32_e32 v214, 16, v31
	v_and_b32_e32 v215, 0xffff0000, v31
	v_cndmask_b32_e32 v62, 0, v62, vcc
	v_cndmask_b32_e32 v63, 0, v63, vcc
	v_lshlrev_b32_e32 v216, 16, v62
	v_and_b32_e32 v217, 0xffff0000, v62
	v_lshlrev_b32_e32 v218, 16, v63
	v_and_b32_e32 v219, 0xffff0000, v63
	v_sub_f32_e32 v216, v216, v212
	v_sub_f32_e32 v217, v217, v213
	v_sub_f32_e32 v218, v218, v214
	v_sub_f32_e32 v219, v219, v215
	v_fmac_f32_e32 v212, v2, v216
	v_fmac_f32_e32 v213, v3, v217
	v_fmac_f32_e32 v214, v4, v218
	v_fmac_f32_e32 v215, v5, v219
	v_mul_f32_e32 v216, v12, v212
	v_mul_f32_e32 v217, v12, v213
	v_mul_f32_e32 v218, v12, v214
	v_mul_f32_e32 v219, v12, v215
	v_exp_f32_e32 v216, v216
	v_exp_f32_e32 v217, v217
	v_exp_f32_e32 v218, v218
	v_exp_f32_e32 v219, v219
	v_add_f32_e32 v216, 1.0, v216
	v_add_f32_e32 v217, 1.0, v217
	v_add_f32_e32 v218, 1.0, v218
	v_add_f32_e32 v219, 1.0, v219
	v_rcp_f32_e32 v216, v216
	v_rcp_f32_e32 v217, v217
	v_rcp_f32_e32 v218, v218
	v_rcp_f32_e32 v219, v219
	v_fma_f32 v216, v216, v13, v14
	v_fma_f32 v217, v217, v13, v14
	v_fma_f32 v218, v218, v13, v14
	v_fma_f32 v219, v219, v13, v14
	v_cndmask_b32_e64 v216, v216, v212, s[42:43]
	v_cndmask_b32_e64 v217, v217, v213, s[42:43]
	v_cndmask_b32_e64 v218, v218, v214, s[42:43]
	v_cndmask_b32_e64 v219, v219, v215, s[42:43]
	v_cvt_pk_bf16_f32 v226, v216, v217
	v_cvt_pk_bf16_f32 v227, v218, v219
	v_ashrrev_i32_e32 v225, 31, v224
	v_lshlrev_b64 v[222:223], 9, v[224:225]
	v_lshl_add_u64 v[222:223], v[8:9], 0, v[222:223]
	global_store_dwordx2 v[222:223], v[226:227], off
	s_waitcnt vmcnt(54)
	v_add_u32_e32 v224, s33, v224
	v_and_b32_e32 v210, 0x7ff, v224
	v_cmp_ne_u32_e32 vcc, 0, v210
	v_lshlrev_b32_e32 v212, 16, v32
	v_and_b32_e32 v213, 0xffff0000, v32
	v_lshlrev_b32_e32 v214, 16, v33
	v_and_b32_e32 v215, 0xffff0000, v33
	v_cndmask_b32_e32 v64, 0, v64, vcc
	v_cndmask_b32_e32 v65, 0, v65, vcc
	v_lshlrev_b32_e32 v216, 16, v64
	v_and_b32_e32 v217, 0xffff0000, v64
	v_lshlrev_b32_e32 v218, 16, v65
	v_and_b32_e32 v219, 0xffff0000, v65
	v_sub_f32_e32 v216, v216, v212
	v_sub_f32_e32 v217, v217, v213
	v_sub_f32_e32 v218, v218, v214
	v_sub_f32_e32 v219, v219, v215
	v_fmac_f32_e32 v212, v2, v216
	v_fmac_f32_e32 v213, v3, v217
	v_fmac_f32_e32 v214, v4, v218
	v_fmac_f32_e32 v215, v5, v219
	v_mul_f32_e32 v216, v12, v212
	v_mul_f32_e32 v217, v12, v213
	v_mul_f32_e32 v218, v12, v214
	v_mul_f32_e32 v219, v12, v215
	v_exp_f32_e32 v216, v216
	v_exp_f32_e32 v217, v217
	v_exp_f32_e32 v218, v218
	v_exp_f32_e32 v219, v219
	v_add_f32_e32 v216, 1.0, v216
	v_add_f32_e32 v217, 1.0, v217
	v_add_f32_e32 v218, 1.0, v218
	v_add_f32_e32 v219, 1.0, v219
	v_rcp_f32_e32 v216, v216
	v_rcp_f32_e32 v217, v217
	v_rcp_f32_e32 v218, v218
	v_rcp_f32_e32 v219, v219
	v_fma_f32 v216, v216, v13, v14
	v_fma_f32 v217, v217, v13, v14
	v_fma_f32 v218, v218, v13, v14
	v_fma_f32 v219, v219, v13, v14
	v_cndmask_b32_e64 v216, v216, v212, s[42:43]
	v_cndmask_b32_e64 v217, v217, v213, s[42:43]
	v_cndmask_b32_e64 v218, v218, v214, s[42:43]
	v_cndmask_b32_e64 v219, v219, v215, s[42:43]
	v_cvt_pk_bf16_f32 v220, v216, v217
	v_cvt_pk_bf16_f32 v221, v218, v219
	v_ashrrev_i32_e32 v225, 31, v224
	v_lshlrev_b64 v[222:223], 9, v[224:225]
	v_lshl_add_u64 v[222:223], v[8:9], 0, v[222:223]
	global_store_dwordx2 v[222:223], v[220:221], off
	s_waitcnt vmcnt(53)
	v_add_u32_e32 v224, s33, v224
	v_and_b32_e32 v210, 0x7ff, v224
	v_cmp_ne_u32_e32 vcc, 0, v210
	v_lshlrev_b32_e32 v212, 16, v34
	v_and_b32_e32 v213, 0xffff0000, v34
	v_lshlrev_b32_e32 v214, 16, v35
	v_and_b32_e32 v215, 0xffff0000, v35
	v_cndmask_b32_e32 v66, 0, v66, vcc
	v_cndmask_b32_e32 v67, 0, v67, vcc
	v_lshlrev_b32_e32 v216, 16, v66
	v_and_b32_e32 v217, 0xffff0000, v66
	v_lshlrev_b32_e32 v218, 16, v67
	v_and_b32_e32 v219, 0xffff0000, v67
	v_sub_f32_e32 v216, v216, v212
	v_sub_f32_e32 v217, v217, v213
	v_sub_f32_e32 v218, v218, v214
	v_sub_f32_e32 v219, v219, v215
	v_fmac_f32_e32 v212, v2, v216
	v_fmac_f32_e32 v213, v3, v217
	v_fmac_f32_e32 v214, v4, v218
	v_fmac_f32_e32 v215, v5, v219
	v_mul_f32_e32 v216, v12, v212
	v_mul_f32_e32 v217, v12, v213
	v_mul_f32_e32 v218, v12, v214
	v_mul_f32_e32 v219, v12, v215
	v_exp_f32_e32 v216, v216
	v_exp_f32_e32 v217, v217
	v_exp_f32_e32 v218, v218
	v_exp_f32_e32 v219, v219
	v_add_f32_e32 v216, 1.0, v216
	v_add_f32_e32 v217, 1.0, v217
	v_add_f32_e32 v218, 1.0, v218
	v_add_f32_e32 v219, 1.0, v219
	v_rcp_f32_e32 v216, v216
	v_rcp_f32_e32 v217, v217
	v_rcp_f32_e32 v218, v218
	v_rcp_f32_e32 v219, v219
	v_fma_f32 v216, v216, v13, v14
	v_fma_f32 v217, v217, v13, v14
	v_fma_f32 v218, v218, v13, v14
	v_fma_f32 v219, v219, v13, v14
	v_cndmask_b32_e64 v216, v216, v212, s[42:43]
	v_cndmask_b32_e64 v217, v217, v213, s[42:43]
	v_cndmask_b32_e64 v218, v218, v214, s[42:43]
	v_cndmask_b32_e64 v219, v219, v215, s[42:43]
	v_cvt_pk_bf16_f32 v226, v216, v217
	v_cvt_pk_bf16_f32 v227, v218, v219
	v_ashrrev_i32_e32 v225, 31, v224
	v_lshlrev_b64 v[222:223], 9, v[224:225]
	v_lshl_add_u64 v[222:223], v[8:9], 0, v[222:223]
	global_store_dwordx2 v[222:223], v[226:227], off
	s_waitcnt vmcnt(52)
	v_add_u32_e32 v224, s33, v224
	v_and_b32_e32 v210, 0x7ff, v224
	v_cmp_ne_u32_e32 vcc, 0, v210
	v_lshlrev_b32_e32 v212, 16, v36
	v_and_b32_e32 v213, 0xffff0000, v36
	v_lshlrev_b32_e32 v214, 16, v37
	v_and_b32_e32 v215, 0xffff0000, v37
	v_cndmask_b32_e32 v68, 0, v68, vcc
	v_cndmask_b32_e32 v69, 0, v69, vcc
	v_lshlrev_b32_e32 v216, 16, v68
	v_and_b32_e32 v217, 0xffff0000, v68
	v_lshlrev_b32_e32 v218, 16, v69
	v_and_b32_e32 v219, 0xffff0000, v69
	v_sub_f32_e32 v216, v216, v212
	v_sub_f32_e32 v217, v217, v213
	v_sub_f32_e32 v218, v218, v214
	v_sub_f32_e32 v219, v219, v215
	v_fmac_f32_e32 v212, v2, v216
	v_fmac_f32_e32 v213, v3, v217
	v_fmac_f32_e32 v214, v4, v218
	v_fmac_f32_e32 v215, v5, v219
	v_mul_f32_e32 v216, v12, v212
	v_mul_f32_e32 v217, v12, v213
	v_mul_f32_e32 v218, v12, v214
	v_mul_f32_e32 v219, v12, v215
	v_exp_f32_e32 v216, v216
	v_exp_f32_e32 v217, v217
	v_exp_f32_e32 v218, v218
	v_exp_f32_e32 v219, v219
	v_add_f32_e32 v216, 1.0, v216
	v_add_f32_e32 v217, 1.0, v217
	v_add_f32_e32 v218, 1.0, v218
	v_add_f32_e32 v219, 1.0, v219
	v_rcp_f32_e32 v216, v216
	v_rcp_f32_e32 v217, v217
	v_rcp_f32_e32 v218, v218
	v_rcp_f32_e32 v219, v219
	v_fma_f32 v216, v216, v13, v14
	v_fma_f32 v217, v217, v13, v14
	v_fma_f32 v218, v218, v13, v14
	v_fma_f32 v219, v219, v13, v14
	v_cndmask_b32_e64 v216, v216, v212, s[42:43]
	v_cndmask_b32_e64 v217, v217, v213, s[42:43]
	v_cndmask_b32_e64 v218, v218, v214, s[42:43]
	v_cndmask_b32_e64 v219, v219, v215, s[42:43]
	v_cvt_pk_bf16_f32 v220, v216, v217
	v_cvt_pk_bf16_f32 v221, v218, v219
	v_ashrrev_i32_e32 v225, 31, v224
	v_lshlrev_b64 v[222:223], 9, v[224:225]
	v_lshl_add_u64 v[222:223], v[8:9], 0, v[222:223]
	global_store_dwordx2 v[222:223], v[220:221], off
	s_waitcnt vmcnt(51)
	v_add_u32_e32 v224, s33, v224
	v_and_b32_e32 v210, 0x7ff, v224
	v_cmp_ne_u32_e32 vcc, 0, v210
	v_lshlrev_b32_e32 v212, 16, v38
	v_and_b32_e32 v213, 0xffff0000, v38
	v_lshlrev_b32_e32 v214, 16, v39
	v_and_b32_e32 v215, 0xffff0000, v39
	v_cndmask_b32_e32 v70, 0, v70, vcc
	v_cndmask_b32_e32 v71, 0, v71, vcc
	v_lshlrev_b32_e32 v216, 16, v70
	v_and_b32_e32 v217, 0xffff0000, v70
	v_lshlrev_b32_e32 v218, 16, v71
	v_and_b32_e32 v219, 0xffff0000, v71
	v_sub_f32_e32 v216, v216, v212
	v_sub_f32_e32 v217, v217, v213
	v_sub_f32_e32 v218, v218, v214
	v_sub_f32_e32 v219, v219, v215
	v_fmac_f32_e32 v212, v2, v216
	v_fmac_f32_e32 v213, v3, v217
	v_fmac_f32_e32 v214, v4, v218
	v_fmac_f32_e32 v215, v5, v219
	v_mul_f32_e32 v216, v12, v212
	v_mul_f32_e32 v217, v12, v213
	v_mul_f32_e32 v218, v12, v214
	v_mul_f32_e32 v219, v12, v215
	v_exp_f32_e32 v216, v216
	v_exp_f32_e32 v217, v217
	v_exp_f32_e32 v218, v218
	v_exp_f32_e32 v219, v219
	v_add_f32_e32 v216, 1.0, v216
	v_add_f32_e32 v217, 1.0, v217
	v_add_f32_e32 v218, 1.0, v218
	v_add_f32_e32 v219, 1.0, v219
	v_rcp_f32_e32 v216, v216
	v_rcp_f32_e32 v217, v217
	v_rcp_f32_e32 v218, v218
	v_rcp_f32_e32 v219, v219
	v_fma_f32 v216, v216, v13, v14
	v_fma_f32 v217, v217, v13, v14
	v_fma_f32 v218, v218, v13, v14
	v_fma_f32 v219, v219, v13, v14
	v_cndmask_b32_e64 v216, v216, v212, s[42:43]
	v_cndmask_b32_e64 v217, v217, v213, s[42:43]
	v_cndmask_b32_e64 v218, v218, v214, s[42:43]
	v_cndmask_b32_e64 v219, v219, v215, s[42:43]
	v_cvt_pk_bf16_f32 v226, v216, v217
	v_cvt_pk_bf16_f32 v227, v218, v219
	v_ashrrev_i32_e32 v225, 31, v224
	v_lshlrev_b64 v[222:223], 9, v[224:225]
	v_lshl_add_u64 v[222:223], v[8:9], 0, v[222:223]
	global_store_dwordx2 v[222:223], v[226:227], off
	s_waitcnt vmcnt(50)
	v_add_u32_e32 v224, s33, v224
	v_and_b32_e32 v210, 0x7ff, v224
	v_cmp_ne_u32_e32 vcc, 0, v210
	v_lshlrev_b32_e32 v212, 16, v40
	v_and_b32_e32 v213, 0xffff0000, v40
	v_lshlrev_b32_e32 v214, 16, v41
	v_and_b32_e32 v215, 0xffff0000, v41
	v_cndmask_b32_e32 v72, 0, v72, vcc
	v_cndmask_b32_e32 v73, 0, v73, vcc
	v_lshlrev_b32_e32 v216, 16, v72
	v_and_b32_e32 v217, 0xffff0000, v72
	v_lshlrev_b32_e32 v218, 16, v73
	v_and_b32_e32 v219, 0xffff0000, v73
	v_sub_f32_e32 v216, v216, v212
	v_sub_f32_e32 v217, v217, v213
	v_sub_f32_e32 v218, v218, v214
	v_sub_f32_e32 v219, v219, v215
	v_fmac_f32_e32 v212, v2, v216
	v_fmac_f32_e32 v213, v3, v217
	v_fmac_f32_e32 v214, v4, v218
	v_fmac_f32_e32 v215, v5, v219
	v_mul_f32_e32 v216, v12, v212
	v_mul_f32_e32 v217, v12, v213
	v_mul_f32_e32 v218, v12, v214
	v_mul_f32_e32 v219, v12, v215
	v_exp_f32_e32 v216, v216
	v_exp_f32_e32 v217, v217
	v_exp_f32_e32 v218, v218
	v_exp_f32_e32 v219, v219
	v_add_f32_e32 v216, 1.0, v216
	v_add_f32_e32 v217, 1.0, v217
	v_add_f32_e32 v218, 1.0, v218
	v_add_f32_e32 v219, 1.0, v219
	v_rcp_f32_e32 v216, v216
	v_rcp_f32_e32 v217, v217
	v_rcp_f32_e32 v218, v218
	v_rcp_f32_e32 v219, v219
	v_fma_f32 v216, v216, v13, v14
	v_fma_f32 v217, v217, v13, v14
	v_fma_f32 v218, v218, v13, v14
	v_fma_f32 v219, v219, v13, v14
	v_cndmask_b32_e64 v216, v216, v212, s[42:43]
	v_cndmask_b32_e64 v217, v217, v213, s[42:43]
	v_cndmask_b32_e64 v218, v218, v214, s[42:43]
	v_cndmask_b32_e64 v219, v219, v215, s[42:43]
	v_cvt_pk_bf16_f32 v220, v216, v217
	v_cvt_pk_bf16_f32 v221, v218, v219
	v_ashrrev_i32_e32 v225, 31, v224
	v_lshlrev_b64 v[222:223], 9, v[224:225]
	v_lshl_add_u64 v[222:223], v[8:9], 0, v[222:223]
	global_store_dwordx2 v[222:223], v[220:221], off
	s_waitcnt vmcnt(49)
	v_add_u32_e32 v224, s33, v224
	v_and_b32_e32 v210, 0x7ff, v224
	v_cmp_ne_u32_e32 vcc, 0, v210
	v_lshlrev_b32_e32 v212, 16, v42
	v_and_b32_e32 v213, 0xffff0000, v42
	v_lshlrev_b32_e32 v214, 16, v43
	v_and_b32_e32 v215, 0xffff0000, v43
	v_cndmask_b32_e32 v74, 0, v74, vcc
	v_cndmask_b32_e32 v75, 0, v75, vcc
	v_lshlrev_b32_e32 v216, 16, v74
	v_and_b32_e32 v217, 0xffff0000, v74
	v_lshlrev_b32_e32 v218, 16, v75
	v_and_b32_e32 v219, 0xffff0000, v75
	v_sub_f32_e32 v216, v216, v212
	v_sub_f32_e32 v217, v217, v213
	v_sub_f32_e32 v218, v218, v214
	v_sub_f32_e32 v219, v219, v215
	v_fmac_f32_e32 v212, v2, v216
	v_fmac_f32_e32 v213, v3, v217
	v_fmac_f32_e32 v214, v4, v218
	v_fmac_f32_e32 v215, v5, v219
	v_mul_f32_e32 v216, v12, v212
	v_mul_f32_e32 v217, v12, v213
	v_mul_f32_e32 v218, v12, v214
	v_mul_f32_e32 v219, v12, v215
	v_exp_f32_e32 v216, v216
	v_exp_f32_e32 v217, v217
	v_exp_f32_e32 v218, v218
	v_exp_f32_e32 v219, v219
	v_add_f32_e32 v216, 1.0, v216
	v_add_f32_e32 v217, 1.0, v217
	v_add_f32_e32 v218, 1.0, v218
	v_add_f32_e32 v219, 1.0, v219
	v_rcp_f32_e32 v216, v216
	v_rcp_f32_e32 v217, v217
	v_rcp_f32_e32 v218, v218
	v_rcp_f32_e32 v219, v219
	v_fma_f32 v216, v216, v13, v14
	v_fma_f32 v217, v217, v13, v14
	v_fma_f32 v218, v218, v13, v14
	v_fma_f32 v219, v219, v13, v14
	v_cndmask_b32_e64 v216, v216, v212, s[42:43]
	v_cndmask_b32_e64 v217, v217, v213, s[42:43]
	v_cndmask_b32_e64 v218, v218, v214, s[42:43]
	v_cndmask_b32_e64 v219, v219, v215, s[42:43]
	v_cvt_pk_bf16_f32 v226, v216, v217
	v_cvt_pk_bf16_f32 v227, v218, v219
	v_ashrrev_i32_e32 v225, 31, v224
	v_lshlrev_b64 v[222:223], 9, v[224:225]
	v_lshl_add_u64 v[222:223], v[8:9], 0, v[222:223]
	global_store_dwordx2 v[222:223], v[226:227], off
	s_waitcnt vmcnt(48)
	v_add_u32_e32 v224, s33, v224
	v_and_b32_e32 v210, 0x7ff, v224
	v_cmp_ne_u32_e32 vcc, 0, v210
	v_lshlrev_b32_e32 v212, 16, v44
	v_and_b32_e32 v213, 0xffff0000, v44
	v_lshlrev_b32_e32 v214, 16, v45
	v_and_b32_e32 v215, 0xffff0000, v45
	v_cndmask_b32_e32 v76, 0, v76, vcc
	v_cndmask_b32_e32 v77, 0, v77, vcc
	v_lshlrev_b32_e32 v216, 16, v76
	v_and_b32_e32 v217, 0xffff0000, v76
	v_lshlrev_b32_e32 v218, 16, v77
	v_and_b32_e32 v219, 0xffff0000, v77
	v_sub_f32_e32 v216, v216, v212
	v_sub_f32_e32 v217, v217, v213
	v_sub_f32_e32 v218, v218, v214
	v_sub_f32_e32 v219, v219, v215
	v_fmac_f32_e32 v212, v2, v216
	v_fmac_f32_e32 v213, v3, v217
	v_fmac_f32_e32 v214, v4, v218
	v_fmac_f32_e32 v215, v5, v219
	v_mul_f32_e32 v216, v12, v212
	v_mul_f32_e32 v217, v12, v213
	v_mul_f32_e32 v218, v12, v214
	v_mul_f32_e32 v219, v12, v215
	v_exp_f32_e32 v216, v216
	v_exp_f32_e32 v217, v217
	v_exp_f32_e32 v218, v218
	v_exp_f32_e32 v219, v219
	v_add_f32_e32 v216, 1.0, v216
	v_add_f32_e32 v217, 1.0, v217
	v_add_f32_e32 v218, 1.0, v218
	v_add_f32_e32 v219, 1.0, v219
	v_rcp_f32_e32 v216, v216
	v_rcp_f32_e32 v217, v217
	v_rcp_f32_e32 v218, v218
	v_rcp_f32_e32 v219, v219
	v_fma_f32 v216, v216, v13, v14
	v_fma_f32 v217, v217, v13, v14
	v_fma_f32 v218, v218, v13, v14
	v_fma_f32 v219, v219, v13, v14
	v_cndmask_b32_e64 v216, v216, v212, s[42:43]
	v_cndmask_b32_e64 v217, v217, v213, s[42:43]
	v_cndmask_b32_e64 v218, v218, v214, s[42:43]
	v_cndmask_b32_e64 v219, v219, v215, s[42:43]
	v_cvt_pk_bf16_f32 v220, v216, v217
	v_cvt_pk_bf16_f32 v221, v218, v219
	v_ashrrev_i32_e32 v225, 31, v224
	v_lshlrev_b64 v[222:223], 9, v[224:225]
	v_lshl_add_u64 v[222:223], v[8:9], 0, v[222:223]
	global_store_dwordx2 v[222:223], v[220:221], off
	s_waitcnt vmcnt(47)
	v_add_u32_e32 v224, s33, v224
	v_and_b32_e32 v210, 0x7ff, v224
	v_cmp_ne_u32_e32 vcc, 0, v210
	v_lshlrev_b32_e32 v212, 16, v46
	v_and_b32_e32 v213, 0xffff0000, v46
	v_lshlrev_b32_e32 v214, 16, v47
	v_and_b32_e32 v215, 0xffff0000, v47
	v_cndmask_b32_e32 v78, 0, v78, vcc
	v_cndmask_b32_e32 v79, 0, v79, vcc
	v_lshlrev_b32_e32 v216, 16, v78
	v_and_b32_e32 v217, 0xffff0000, v78
	v_lshlrev_b32_e32 v218, 16, v79
	v_and_b32_e32 v219, 0xffff0000, v79
	v_sub_f32_e32 v216, v216, v212
	v_sub_f32_e32 v217, v217, v213
	v_sub_f32_e32 v218, v218, v214
	v_sub_f32_e32 v219, v219, v215
	v_fmac_f32_e32 v212, v2, v216
	v_fmac_f32_e32 v213, v3, v217
	v_fmac_f32_e32 v214, v4, v218
	v_fmac_f32_e32 v215, v5, v219
	v_mul_f32_e32 v216, v12, v212
	v_mul_f32_e32 v217, v12, v213
	v_mul_f32_e32 v218, v12, v214
	v_mul_f32_e32 v219, v12, v215
	v_exp_f32_e32 v216, v216
	v_exp_f32_e32 v217, v217
	v_exp_f32_e32 v218, v218
	v_exp_f32_e32 v219, v219
	v_add_f32_e32 v216, 1.0, v216
	v_add_f32_e32 v217, 1.0, v217
	v_add_f32_e32 v218, 1.0, v218
	v_add_f32_e32 v219, 1.0, v219
	v_rcp_f32_e32 v216, v216
	v_rcp_f32_e32 v217, v217
	v_rcp_f32_e32 v218, v218
	v_rcp_f32_e32 v219, v219
	v_fma_f32 v216, v216, v13, v14
	v_fma_f32 v217, v217, v13, v14
	v_fma_f32 v218, v218, v13, v14
	v_fma_f32 v219, v219, v13, v14
	v_cndmask_b32_e64 v216, v216, v212, s[42:43]
	v_cndmask_b32_e64 v217, v217, v213, s[42:43]
	v_cndmask_b32_e64 v218, v218, v214, s[42:43]
	v_cndmask_b32_e64 v219, v219, v215, s[42:43]
	v_cvt_pk_bf16_f32 v226, v216, v217
	v_cvt_pk_bf16_f32 v227, v218, v219
	v_ashrrev_i32_e32 v225, 31, v224
	v_lshlrev_b64 v[222:223], 9, v[224:225]
	v_lshl_add_u64 v[222:223], v[8:9], 0, v[222:223]
	global_store_dwordx2 v[222:223], v[226:227], off
	s_waitcnt vmcnt(46)
	v_add_u32_e32 v224, s33, v224
	v_and_b32_e32 v210, 0x7ff, v224
	v_cmp_ne_u32_e32 vcc, 0, v210
	v_lshlrev_b32_e32 v212, 16, v80
	v_and_b32_e32 v213, 0xffff0000, v80
	v_lshlrev_b32_e32 v214, 16, v81
	v_and_b32_e32 v215, 0xffff0000, v81
	v_cndmask_b32_e32 v112, 0, v112, vcc
	v_cndmask_b32_e32 v113, 0, v113, vcc
	v_lshlrev_b32_e32 v216, 16, v112
	v_and_b32_e32 v217, 0xffff0000, v112
	v_lshlrev_b32_e32 v218, 16, v113
	v_and_b32_e32 v219, 0xffff0000, v113
	v_sub_f32_e32 v216, v216, v212
	v_sub_f32_e32 v217, v217, v213
	v_sub_f32_e32 v218, v218, v214
	v_sub_f32_e32 v219, v219, v215
	v_fmac_f32_e32 v212, v2, v216
	v_fmac_f32_e32 v213, v3, v217
	v_fmac_f32_e32 v214, v4, v218
	v_fmac_f32_e32 v215, v5, v219
	v_mul_f32_e32 v216, v12, v212
	v_mul_f32_e32 v217, v12, v213
	v_mul_f32_e32 v218, v12, v214
	v_mul_f32_e32 v219, v12, v215
	v_exp_f32_e32 v216, v216
	v_exp_f32_e32 v217, v217
	v_exp_f32_e32 v218, v218
	v_exp_f32_e32 v219, v219
	v_add_f32_e32 v216, 1.0, v216
	v_add_f32_e32 v217, 1.0, v217
	v_add_f32_e32 v218, 1.0, v218
	v_add_f32_e32 v219, 1.0, v219
	v_rcp_f32_e32 v216, v216
	v_rcp_f32_e32 v217, v217
	v_rcp_f32_e32 v218, v218
	v_rcp_f32_e32 v219, v219
	v_fma_f32 v216, v216, v13, v14
	v_fma_f32 v217, v217, v13, v14
	v_fma_f32 v218, v218, v13, v14
	v_fma_f32 v219, v219, v13, v14
	v_cndmask_b32_e64 v216, v216, v212, s[42:43]
	v_cndmask_b32_e64 v217, v217, v213, s[42:43]
	v_cndmask_b32_e64 v218, v218, v214, s[42:43]
	v_cndmask_b32_e64 v219, v219, v215, s[42:43]
	v_cvt_pk_bf16_f32 v220, v216, v217
	v_cvt_pk_bf16_f32 v221, v218, v219
	v_ashrrev_i32_e32 v225, 31, v224
	v_lshlrev_b64 v[222:223], 9, v[224:225]
	v_lshl_add_u64 v[222:223], v[8:9], 0, v[222:223]
	global_store_dwordx2 v[222:223], v[220:221], off
	s_waitcnt vmcnt(45)
	v_add_u32_e32 v224, s33, v224
	v_and_b32_e32 v210, 0x7ff, v224
	v_cmp_ne_u32_e32 vcc, 0, v210
	v_lshlrev_b32_e32 v212, 16, v82
	v_and_b32_e32 v213, 0xffff0000, v82
	v_lshlrev_b32_e32 v214, 16, v83
	v_and_b32_e32 v215, 0xffff0000, v83
	v_cndmask_b32_e32 v114, 0, v114, vcc
	v_cndmask_b32_e32 v115, 0, v115, vcc
	v_lshlrev_b32_e32 v216, 16, v114
	v_and_b32_e32 v217, 0xffff0000, v114
	v_lshlrev_b32_e32 v218, 16, v115
	v_and_b32_e32 v219, 0xffff0000, v115
	v_sub_f32_e32 v216, v216, v212
	v_sub_f32_e32 v217, v217, v213
	v_sub_f32_e32 v218, v218, v214
	v_sub_f32_e32 v219, v219, v215
	v_fmac_f32_e32 v212, v2, v216
	v_fmac_f32_e32 v213, v3, v217
	v_fmac_f32_e32 v214, v4, v218
	v_fmac_f32_e32 v215, v5, v219
	v_mul_f32_e32 v216, v12, v212
	v_mul_f32_e32 v217, v12, v213
	v_mul_f32_e32 v218, v12, v214
	v_mul_f32_e32 v219, v12, v215
	v_exp_f32_e32 v216, v216
	v_exp_f32_e32 v217, v217
	v_exp_f32_e32 v218, v218
	v_exp_f32_e32 v219, v219
	v_add_f32_e32 v216, 1.0, v216
	v_add_f32_e32 v217, 1.0, v217
	v_add_f32_e32 v218, 1.0, v218
	v_add_f32_e32 v219, 1.0, v219
	v_rcp_f32_e32 v216, v216
	v_rcp_f32_e32 v217, v217
	v_rcp_f32_e32 v218, v218
	v_rcp_f32_e32 v219, v219
	v_fma_f32 v216, v216, v13, v14
	v_fma_f32 v217, v217, v13, v14
	v_fma_f32 v218, v218, v13, v14
	v_fma_f32 v219, v219, v13, v14
	v_cndmask_b32_e64 v216, v216, v212, s[42:43]
	v_cndmask_b32_e64 v217, v217, v213, s[42:43]
	v_cndmask_b32_e64 v218, v218, v214, s[42:43]
	v_cndmask_b32_e64 v219, v219, v215, s[42:43]
	v_cvt_pk_bf16_f32 v226, v216, v217
	v_cvt_pk_bf16_f32 v227, v218, v219
	v_ashrrev_i32_e32 v225, 31, v224
	v_lshlrev_b64 v[222:223], 9, v[224:225]
	v_lshl_add_u64 v[222:223], v[8:9], 0, v[222:223]
	global_store_dwordx2 v[222:223], v[226:227], off
	s_waitcnt vmcnt(44)
	v_add_u32_e32 v224, s33, v224
	v_and_b32_e32 v210, 0x7ff, v224
	v_cmp_ne_u32_e32 vcc, 0, v210
	v_lshlrev_b32_e32 v212, 16, v84
	v_and_b32_e32 v213, 0xffff0000, v84
	v_lshlrev_b32_e32 v214, 16, v85
	v_and_b32_e32 v215, 0xffff0000, v85
	v_cndmask_b32_e32 v116, 0, v116, vcc
	v_cndmask_b32_e32 v117, 0, v117, vcc
	v_lshlrev_b32_e32 v216, 16, v116
	v_and_b32_e32 v217, 0xffff0000, v116
	v_lshlrev_b32_e32 v218, 16, v117
	v_and_b32_e32 v219, 0xffff0000, v117
	v_sub_f32_e32 v216, v216, v212
	v_sub_f32_e32 v217, v217, v213
	v_sub_f32_e32 v218, v218, v214
	v_sub_f32_e32 v219, v219, v215
	v_fmac_f32_e32 v212, v2, v216
	v_fmac_f32_e32 v213, v3, v217
	v_fmac_f32_e32 v214, v4, v218
	v_fmac_f32_e32 v215, v5, v219
	v_mul_f32_e32 v216, v12, v212
	v_mul_f32_e32 v217, v12, v213
	v_mul_f32_e32 v218, v12, v214
	v_mul_f32_e32 v219, v12, v215
	v_exp_f32_e32 v216, v216
	v_exp_f32_e32 v217, v217
	v_exp_f32_e32 v218, v218
	v_exp_f32_e32 v219, v219
	v_add_f32_e32 v216, 1.0, v216
	v_add_f32_e32 v217, 1.0, v217
	v_add_f32_e32 v218, 1.0, v218
	v_add_f32_e32 v219, 1.0, v219
	v_rcp_f32_e32 v216, v216
	v_rcp_f32_e32 v217, v217
	v_rcp_f32_e32 v218, v218
	v_rcp_f32_e32 v219, v219
	v_fma_f32 v216, v216, v13, v14
	v_fma_f32 v217, v217, v13, v14
	v_fma_f32 v218, v218, v13, v14
	v_fma_f32 v219, v219, v13, v14
	v_cndmask_b32_e64 v216, v216, v212, s[42:43]
	v_cndmask_b32_e64 v217, v217, v213, s[42:43]
	v_cndmask_b32_e64 v218, v218, v214, s[42:43]
	v_cndmask_b32_e64 v219, v219, v215, s[42:43]
	v_cvt_pk_bf16_f32 v220, v216, v217
	v_cvt_pk_bf16_f32 v221, v218, v219
	v_ashrrev_i32_e32 v225, 31, v224
	v_lshlrev_b64 v[222:223], 9, v[224:225]
	v_lshl_add_u64 v[222:223], v[8:9], 0, v[222:223]
	global_store_dwordx2 v[222:223], v[220:221], off
	s_waitcnt vmcnt(43)
	v_add_u32_e32 v224, s33, v224
	v_and_b32_e32 v210, 0x7ff, v224
	v_cmp_ne_u32_e32 vcc, 0, v210
	v_lshlrev_b32_e32 v212, 16, v86
	v_and_b32_e32 v213, 0xffff0000, v86
	v_lshlrev_b32_e32 v214, 16, v87
	v_and_b32_e32 v215, 0xffff0000, v87
	v_cndmask_b32_e32 v118, 0, v118, vcc
	v_cndmask_b32_e32 v119, 0, v119, vcc
	v_lshlrev_b32_e32 v216, 16, v118
	v_and_b32_e32 v217, 0xffff0000, v118
	v_lshlrev_b32_e32 v218, 16, v119
	v_and_b32_e32 v219, 0xffff0000, v119
	v_sub_f32_e32 v216, v216, v212
	v_sub_f32_e32 v217, v217, v213
	v_sub_f32_e32 v218, v218, v214
	v_sub_f32_e32 v219, v219, v215
	v_fmac_f32_e32 v212, v2, v216
	v_fmac_f32_e32 v213, v3, v217
	v_fmac_f32_e32 v214, v4, v218
	v_fmac_f32_e32 v215, v5, v219
	v_mul_f32_e32 v216, v12, v212
	v_mul_f32_e32 v217, v12, v213
	v_mul_f32_e32 v218, v12, v214
	v_mul_f32_e32 v219, v12, v215
	v_exp_f32_e32 v216, v216
	v_exp_f32_e32 v217, v217
	v_exp_f32_e32 v218, v218
	v_exp_f32_e32 v219, v219
	v_add_f32_e32 v216, 1.0, v216
	v_add_f32_e32 v217, 1.0, v217
	v_add_f32_e32 v218, 1.0, v218
	v_add_f32_e32 v219, 1.0, v219
	v_rcp_f32_e32 v216, v216
	v_rcp_f32_e32 v217, v217
	v_rcp_f32_e32 v218, v218
	v_rcp_f32_e32 v219, v219
	v_fma_f32 v216, v216, v13, v14
	v_fma_f32 v217, v217, v13, v14
	v_fma_f32 v218, v218, v13, v14
	v_fma_f32 v219, v219, v13, v14
	v_cndmask_b32_e64 v216, v216, v212, s[42:43]
	v_cndmask_b32_e64 v217, v217, v213, s[42:43]
	v_cndmask_b32_e64 v218, v218, v214, s[42:43]
	v_cndmask_b32_e64 v219, v219, v215, s[42:43]
	v_cvt_pk_bf16_f32 v226, v216, v217
	v_cvt_pk_bf16_f32 v227, v218, v219
	v_ashrrev_i32_e32 v225, 31, v224
	v_lshlrev_b64 v[222:223], 9, v[224:225]
	v_lshl_add_u64 v[222:223], v[8:9], 0, v[222:223]
	global_store_dwordx2 v[222:223], v[226:227], off
	s_waitcnt vmcnt(42)
	v_add_u32_e32 v224, s33, v224
	v_and_b32_e32 v210, 0x7ff, v224
	v_cmp_ne_u32_e32 vcc, 0, v210
	v_lshlrev_b32_e32 v212, 16, v88
	v_and_b32_e32 v213, 0xffff0000, v88
	v_lshlrev_b32_e32 v214, 16, v89
	v_and_b32_e32 v215, 0xffff0000, v89
	v_cndmask_b32_e32 v120, 0, v120, vcc
	v_cndmask_b32_e32 v121, 0, v121, vcc
	v_lshlrev_b32_e32 v216, 16, v120
	v_and_b32_e32 v217, 0xffff0000, v120
	v_lshlrev_b32_e32 v218, 16, v121
	v_and_b32_e32 v219, 0xffff0000, v121
	v_sub_f32_e32 v216, v216, v212
	v_sub_f32_e32 v217, v217, v213
	v_sub_f32_e32 v218, v218, v214
	v_sub_f32_e32 v219, v219, v215
	v_fmac_f32_e32 v212, v2, v216
	v_fmac_f32_e32 v213, v3, v217
	v_fmac_f32_e32 v214, v4, v218
	v_fmac_f32_e32 v215, v5, v219
	v_mul_f32_e32 v216, v12, v212
	v_mul_f32_e32 v217, v12, v213
	v_mul_f32_e32 v218, v12, v214
	v_mul_f32_e32 v219, v12, v215
	v_exp_f32_e32 v216, v216
	v_exp_f32_e32 v217, v217
	v_exp_f32_e32 v218, v218
	v_exp_f32_e32 v219, v219
	v_add_f32_e32 v216, 1.0, v216
	v_add_f32_e32 v217, 1.0, v217
	v_add_f32_e32 v218, 1.0, v218
	v_add_f32_e32 v219, 1.0, v219
	v_rcp_f32_e32 v216, v216
	v_rcp_f32_e32 v217, v217
	v_rcp_f32_e32 v218, v218
	v_rcp_f32_e32 v219, v219
	v_fma_f32 v216, v216, v13, v14
	v_fma_f32 v217, v217, v13, v14
	v_fma_f32 v218, v218, v13, v14
	v_fma_f32 v219, v219, v13, v14
	v_cndmask_b32_e64 v216, v216, v212, s[42:43]
	v_cndmask_b32_e64 v217, v217, v213, s[42:43]
	v_cndmask_b32_e64 v218, v218, v214, s[42:43]
	v_cndmask_b32_e64 v219, v219, v215, s[42:43]
	v_cvt_pk_bf16_f32 v220, v216, v217
	v_cvt_pk_bf16_f32 v221, v218, v219
	v_ashrrev_i32_e32 v225, 31, v224
	v_lshlrev_b64 v[222:223], 9, v[224:225]
	v_lshl_add_u64 v[222:223], v[8:9], 0, v[222:223]
	global_store_dwordx2 v[222:223], v[220:221], off
	s_waitcnt vmcnt(41)
	v_add_u32_e32 v224, s33, v224
	v_and_b32_e32 v210, 0x7ff, v224
	v_cmp_ne_u32_e32 vcc, 0, v210
	v_lshlrev_b32_e32 v212, 16, v90
	v_and_b32_e32 v213, 0xffff0000, v90
	v_lshlrev_b32_e32 v214, 16, v91
	v_and_b32_e32 v215, 0xffff0000, v91
	v_cndmask_b32_e32 v122, 0, v122, vcc
	v_cndmask_b32_e32 v123, 0, v123, vcc
	v_lshlrev_b32_e32 v216, 16, v122
	v_and_b32_e32 v217, 0xffff0000, v122
	v_lshlrev_b32_e32 v218, 16, v123
	v_and_b32_e32 v219, 0xffff0000, v123
	v_sub_f32_e32 v216, v216, v212
	v_sub_f32_e32 v217, v217, v213
	v_sub_f32_e32 v218, v218, v214
	v_sub_f32_e32 v219, v219, v215
	v_fmac_f32_e32 v212, v2, v216
	v_fmac_f32_e32 v213, v3, v217
	v_fmac_f32_e32 v214, v4, v218
	v_fmac_f32_e32 v215, v5, v219
	v_mul_f32_e32 v216, v12, v212
	v_mul_f32_e32 v217, v12, v213
	v_mul_f32_e32 v218, v12, v214
	v_mul_f32_e32 v219, v12, v215
	v_exp_f32_e32 v216, v216
	v_exp_f32_e32 v217, v217
	v_exp_f32_e32 v218, v218
	v_exp_f32_e32 v219, v219
	v_add_f32_e32 v216, 1.0, v216
	v_add_f32_e32 v217, 1.0, v217
	v_add_f32_e32 v218, 1.0, v218
	v_add_f32_e32 v219, 1.0, v219
	v_rcp_f32_e32 v216, v216
	v_rcp_f32_e32 v217, v217
	v_rcp_f32_e32 v218, v218
	v_rcp_f32_e32 v219, v219
	v_fma_f32 v216, v216, v13, v14
	v_fma_f32 v217, v217, v13, v14
	v_fma_f32 v218, v218, v13, v14
	v_fma_f32 v219, v219, v13, v14
	v_cndmask_b32_e64 v216, v216, v212, s[42:43]
	v_cndmask_b32_e64 v217, v217, v213, s[42:43]
	v_cndmask_b32_e64 v218, v218, v214, s[42:43]
	v_cndmask_b32_e64 v219, v219, v215, s[42:43]
	v_cvt_pk_bf16_f32 v226, v216, v217
	v_cvt_pk_bf16_f32 v227, v218, v219
	v_ashrrev_i32_e32 v225, 31, v224
	v_lshlrev_b64 v[222:223], 9, v[224:225]
	v_lshl_add_u64 v[222:223], v[8:9], 0, v[222:223]
	global_store_dwordx2 v[222:223], v[226:227], off
	s_waitcnt vmcnt(40)
	v_add_u32_e32 v224, s33, v224
	v_and_b32_e32 v210, 0x7ff, v224
	v_cmp_ne_u32_e32 vcc, 0, v210
	v_lshlrev_b32_e32 v212, 16, v92
	v_and_b32_e32 v213, 0xffff0000, v92
	v_lshlrev_b32_e32 v214, 16, v93
	v_and_b32_e32 v215, 0xffff0000, v93
	v_cndmask_b32_e32 v124, 0, v124, vcc
	v_cndmask_b32_e32 v125, 0, v125, vcc
	v_lshlrev_b32_e32 v216, 16, v124
	v_and_b32_e32 v217, 0xffff0000, v124
	v_lshlrev_b32_e32 v218, 16, v125
	v_and_b32_e32 v219, 0xffff0000, v125
	v_sub_f32_e32 v216, v216, v212
	v_sub_f32_e32 v217, v217, v213
	v_sub_f32_e32 v218, v218, v214
	v_sub_f32_e32 v219, v219, v215
	v_fmac_f32_e32 v212, v2, v216
	v_fmac_f32_e32 v213, v3, v217
	v_fmac_f32_e32 v214, v4, v218
	v_fmac_f32_e32 v215, v5, v219
	v_mul_f32_e32 v216, v12, v212
	v_mul_f32_e32 v217, v12, v213
	v_mul_f32_e32 v218, v12, v214
	v_mul_f32_e32 v219, v12, v215
	v_exp_f32_e32 v216, v216
	v_exp_f32_e32 v217, v217
	v_exp_f32_e32 v218, v218
	v_exp_f32_e32 v219, v219
	v_add_f32_e32 v216, 1.0, v216
	v_add_f32_e32 v217, 1.0, v217
	v_add_f32_e32 v218, 1.0, v218
	v_add_f32_e32 v219, 1.0, v219
	v_rcp_f32_e32 v216, v216
	v_rcp_f32_e32 v217, v217
	v_rcp_f32_e32 v218, v218
	v_rcp_f32_e32 v219, v219
	v_fma_f32 v216, v216, v13, v14
	v_fma_f32 v217, v217, v13, v14
	v_fma_f32 v218, v218, v13, v14
	v_fma_f32 v219, v219, v13, v14
	v_cndmask_b32_e64 v216, v216, v212, s[42:43]
	v_cndmask_b32_e64 v217, v217, v213, s[42:43]
	v_cndmask_b32_e64 v218, v218, v214, s[42:43]
	v_cndmask_b32_e64 v219, v219, v215, s[42:43]
	v_cvt_pk_bf16_f32 v220, v216, v217
	v_cvt_pk_bf16_f32 v221, v218, v219
	v_ashrrev_i32_e32 v225, 31, v224
	v_lshlrev_b64 v[222:223], 9, v[224:225]
	v_lshl_add_u64 v[222:223], v[8:9], 0, v[222:223]
	global_store_dwordx2 v[222:223], v[220:221], off
	s_waitcnt vmcnt(39)
	v_add_u32_e32 v224, s33, v224
	v_and_b32_e32 v210, 0x7ff, v224
	v_cmp_ne_u32_e32 vcc, 0, v210
	v_lshlrev_b32_e32 v212, 16, v94
	v_and_b32_e32 v213, 0xffff0000, v94
	v_lshlrev_b32_e32 v214, 16, v95
	v_and_b32_e32 v215, 0xffff0000, v95
	v_cndmask_b32_e32 v126, 0, v126, vcc
	v_cndmask_b32_e32 v127, 0, v127, vcc
	v_lshlrev_b32_e32 v216, 16, v126
	v_and_b32_e32 v217, 0xffff0000, v126
	v_lshlrev_b32_e32 v218, 16, v127
	v_and_b32_e32 v219, 0xffff0000, v127
	v_sub_f32_e32 v216, v216, v212
	v_sub_f32_e32 v217, v217, v213
	v_sub_f32_e32 v218, v218, v214
	v_sub_f32_e32 v219, v219, v215
	v_fmac_f32_e32 v212, v2, v216
	v_fmac_f32_e32 v213, v3, v217
	v_fmac_f32_e32 v214, v4, v218
	v_fmac_f32_e32 v215, v5, v219
	v_mul_f32_e32 v216, v12, v212
	v_mul_f32_e32 v217, v12, v213
	v_mul_f32_e32 v218, v12, v214
	v_mul_f32_e32 v219, v12, v215
	v_exp_f32_e32 v216, v216
	v_exp_f32_e32 v217, v217
	v_exp_f32_e32 v218, v218
	v_exp_f32_e32 v219, v219
	v_add_f32_e32 v216, 1.0, v216
	v_add_f32_e32 v217, 1.0, v217
	v_add_f32_e32 v218, 1.0, v218
	v_add_f32_e32 v219, 1.0, v219
	v_rcp_f32_e32 v216, v216
	v_rcp_f32_e32 v217, v217
	v_rcp_f32_e32 v218, v218
	v_rcp_f32_e32 v219, v219
	v_fma_f32 v216, v216, v13, v14
	v_fma_f32 v217, v217, v13, v14
	v_fma_f32 v218, v218, v13, v14
	v_fma_f32 v219, v219, v13, v14
	v_cndmask_b32_e64 v216, v216, v212, s[42:43]
	v_cndmask_b32_e64 v217, v217, v213, s[42:43]
	v_cndmask_b32_e64 v218, v218, v214, s[42:43]
	v_cndmask_b32_e64 v219, v219, v215, s[42:43]
	v_cvt_pk_bf16_f32 v226, v216, v217
	v_cvt_pk_bf16_f32 v227, v218, v219
	v_ashrrev_i32_e32 v225, 31, v224
	v_lshlrev_b64 v[222:223], 9, v[224:225]
	v_lshl_add_u64 v[222:223], v[8:9], 0, v[222:223]
	global_store_dwordx2 v[222:223], v[226:227], off
	s_waitcnt vmcnt(38)
	v_add_u32_e32 v224, s33, v224
	v_and_b32_e32 v210, 0x7ff, v224
	v_cmp_ne_u32_e32 vcc, 0, v210
	v_lshlrev_b32_e32 v212, 16, v96
	v_and_b32_e32 v213, 0xffff0000, v96
	v_lshlrev_b32_e32 v214, 16, v97
	v_and_b32_e32 v215, 0xffff0000, v97
	v_cndmask_b32_e32 v128, 0, v128, vcc
	v_cndmask_b32_e32 v129, 0, v129, vcc
	v_lshlrev_b32_e32 v216, 16, v128
	v_and_b32_e32 v217, 0xffff0000, v128
	v_lshlrev_b32_e32 v218, 16, v129
	v_and_b32_e32 v219, 0xffff0000, v129
	v_sub_f32_e32 v216, v216, v212
	v_sub_f32_e32 v217, v217, v213
	v_sub_f32_e32 v218, v218, v214
	v_sub_f32_e32 v219, v219, v215
	v_fmac_f32_e32 v212, v2, v216
	v_fmac_f32_e32 v213, v3, v217
	v_fmac_f32_e32 v214, v4, v218
	v_fmac_f32_e32 v215, v5, v219
	v_mul_f32_e32 v216, v12, v212
	v_mul_f32_e32 v217, v12, v213
	v_mul_f32_e32 v218, v12, v214
	v_mul_f32_e32 v219, v12, v215
	v_exp_f32_e32 v216, v216
	v_exp_f32_e32 v217, v217
	v_exp_f32_e32 v218, v218
	v_exp_f32_e32 v219, v219
	v_add_f32_e32 v216, 1.0, v216
	v_add_f32_e32 v217, 1.0, v217
	v_add_f32_e32 v218, 1.0, v218
	v_add_f32_e32 v219, 1.0, v219
	v_rcp_f32_e32 v216, v216
	v_rcp_f32_e32 v217, v217
	v_rcp_f32_e32 v218, v218
	v_rcp_f32_e32 v219, v219
	v_fma_f32 v216, v216, v13, v14
	v_fma_f32 v217, v217, v13, v14
	v_fma_f32 v218, v218, v13, v14
	v_fma_f32 v219, v219, v13, v14
	v_cndmask_b32_e64 v216, v216, v212, s[42:43]
	v_cndmask_b32_e64 v217, v217, v213, s[42:43]
	v_cndmask_b32_e64 v218, v218, v214, s[42:43]
	v_cndmask_b32_e64 v219, v219, v215, s[42:43]
	v_cvt_pk_bf16_f32 v220, v216, v217
	v_cvt_pk_bf16_f32 v221, v218, v219
	v_ashrrev_i32_e32 v225, 31, v224
	v_lshlrev_b64 v[222:223], 9, v[224:225]
	v_lshl_add_u64 v[222:223], v[8:9], 0, v[222:223]
	global_store_dwordx2 v[222:223], v[220:221], off
	s_waitcnt vmcnt(37)
	v_add_u32_e32 v224, s33, v224
	v_and_b32_e32 v210, 0x7ff, v224
	v_cmp_ne_u32_e32 vcc, 0, v210
	v_lshlrev_b32_e32 v212, 16, v98
	v_and_b32_e32 v213, 0xffff0000, v98
	v_lshlrev_b32_e32 v214, 16, v99
	v_and_b32_e32 v215, 0xffff0000, v99
	v_cndmask_b32_e32 v130, 0, v130, vcc
	v_cndmask_b32_e32 v131, 0, v131, vcc
	v_lshlrev_b32_e32 v216, 16, v130
	v_and_b32_e32 v217, 0xffff0000, v130
	v_lshlrev_b32_e32 v218, 16, v131
	v_and_b32_e32 v219, 0xffff0000, v131
	v_sub_f32_e32 v216, v216, v212
	v_sub_f32_e32 v217, v217, v213
	v_sub_f32_e32 v218, v218, v214
	v_sub_f32_e32 v219, v219, v215
	v_fmac_f32_e32 v212, v2, v216
	v_fmac_f32_e32 v213, v3, v217
	v_fmac_f32_e32 v214, v4, v218
	v_fmac_f32_e32 v215, v5, v219
	v_mul_f32_e32 v216, v12, v212
	v_mul_f32_e32 v217, v12, v213
	v_mul_f32_e32 v218, v12, v214
	v_mul_f32_e32 v219, v12, v215
	v_exp_f32_e32 v216, v216
	v_exp_f32_e32 v217, v217
	v_exp_f32_e32 v218, v218
	v_exp_f32_e32 v219, v219
	v_add_f32_e32 v216, 1.0, v216
	v_add_f32_e32 v217, 1.0, v217
	v_add_f32_e32 v218, 1.0, v218
	v_add_f32_e32 v219, 1.0, v219
	v_rcp_f32_e32 v216, v216
	v_rcp_f32_e32 v217, v217
	v_rcp_f32_e32 v218, v218
	v_rcp_f32_e32 v219, v219
	v_fma_f32 v216, v216, v13, v14
	v_fma_f32 v217, v217, v13, v14
	v_fma_f32 v218, v218, v13, v14
	v_fma_f32 v219, v219, v13, v14
	v_cndmask_b32_e64 v216, v216, v212, s[42:43]
	v_cndmask_b32_e64 v217, v217, v213, s[42:43]
	v_cndmask_b32_e64 v218, v218, v214, s[42:43]
	v_cndmask_b32_e64 v219, v219, v215, s[42:43]
	v_cvt_pk_bf16_f32 v226, v216, v217
	v_cvt_pk_bf16_f32 v227, v218, v219
	v_ashrrev_i32_e32 v225, 31, v224
	v_lshlrev_b64 v[222:223], 9, v[224:225]
	v_lshl_add_u64 v[222:223], v[8:9], 0, v[222:223]
	global_store_dwordx2 v[222:223], v[226:227], off
	s_waitcnt vmcnt(36)
	v_add_u32_e32 v224, s33, v224
	v_and_b32_e32 v210, 0x7ff, v224
	v_cmp_ne_u32_e32 vcc, 0, v210
	v_lshlrev_b32_e32 v212, 16, v100
	v_and_b32_e32 v213, 0xffff0000, v100
	v_lshlrev_b32_e32 v214, 16, v101
	v_and_b32_e32 v215, 0xffff0000, v101
	v_cndmask_b32_e32 v132, 0, v132, vcc
	v_cndmask_b32_e32 v133, 0, v133, vcc
	v_lshlrev_b32_e32 v216, 16, v132
	v_and_b32_e32 v217, 0xffff0000, v132
	v_lshlrev_b32_e32 v218, 16, v133
	v_and_b32_e32 v219, 0xffff0000, v133
	v_sub_f32_e32 v216, v216, v212
	v_sub_f32_e32 v217, v217, v213
	v_sub_f32_e32 v218, v218, v214
	v_sub_f32_e32 v219, v219, v215
	v_fmac_f32_e32 v212, v2, v216
	v_fmac_f32_e32 v213, v3, v217
	v_fmac_f32_e32 v214, v4, v218
	v_fmac_f32_e32 v215, v5, v219
	v_mul_f32_e32 v216, v12, v212
	v_mul_f32_e32 v217, v12, v213
	v_mul_f32_e32 v218, v12, v214
	v_mul_f32_e32 v219, v12, v215
	v_exp_f32_e32 v216, v216
	v_exp_f32_e32 v217, v217
	v_exp_f32_e32 v218, v218
	v_exp_f32_e32 v219, v219
	v_add_f32_e32 v216, 1.0, v216
	v_add_f32_e32 v217, 1.0, v217
	v_add_f32_e32 v218, 1.0, v218
	v_add_f32_e32 v219, 1.0, v219
	v_rcp_f32_e32 v216, v216
	v_rcp_f32_e32 v217, v217
	v_rcp_f32_e32 v218, v218
	v_rcp_f32_e32 v219, v219
	v_fma_f32 v216, v216, v13, v14
	v_fma_f32 v217, v217, v13, v14
	v_fma_f32 v218, v218, v13, v14
	v_fma_f32 v219, v219, v13, v14
	v_cndmask_b32_e64 v216, v216, v212, s[42:43]
	v_cndmask_b32_e64 v217, v217, v213, s[42:43]
	v_cndmask_b32_e64 v218, v218, v214, s[42:43]
	v_cndmask_b32_e64 v219, v219, v215, s[42:43]
	v_cvt_pk_bf16_f32 v220, v216, v217
	v_cvt_pk_bf16_f32 v221, v218, v219
	v_ashrrev_i32_e32 v225, 31, v224
	v_lshlrev_b64 v[222:223], 9, v[224:225]
	v_lshl_add_u64 v[222:223], v[8:9], 0, v[222:223]
	global_store_dwordx2 v[222:223], v[220:221], off
	s_waitcnt vmcnt(35)
	v_add_u32_e32 v224, s33, v224
	v_and_b32_e32 v210, 0x7ff, v224
	v_cmp_ne_u32_e32 vcc, 0, v210
	v_lshlrev_b32_e32 v212, 16, v102
	v_and_b32_e32 v213, 0xffff0000, v102
	v_lshlrev_b32_e32 v214, 16, v103
	v_and_b32_e32 v215, 0xffff0000, v103
	v_cndmask_b32_e32 v134, 0, v134, vcc
	v_cndmask_b32_e32 v135, 0, v135, vcc
	v_lshlrev_b32_e32 v216, 16, v134
	v_and_b32_e32 v217, 0xffff0000, v134
	v_lshlrev_b32_e32 v218, 16, v135
	v_and_b32_e32 v219, 0xffff0000, v135
	v_sub_f32_e32 v216, v216, v212
	v_sub_f32_e32 v217, v217, v213
	v_sub_f32_e32 v218, v218, v214
	v_sub_f32_e32 v219, v219, v215
	v_fmac_f32_e32 v212, v2, v216
	v_fmac_f32_e32 v213, v3, v217
	v_fmac_f32_e32 v214, v4, v218
	v_fmac_f32_e32 v215, v5, v219
	v_mul_f32_e32 v216, v12, v212
	v_mul_f32_e32 v217, v12, v213
	v_mul_f32_e32 v218, v12, v214
	v_mul_f32_e32 v219, v12, v215
	v_exp_f32_e32 v216, v216
	v_exp_f32_e32 v217, v217
	v_exp_f32_e32 v218, v218
	v_exp_f32_e32 v219, v219
	v_add_f32_e32 v216, 1.0, v216
	v_add_f32_e32 v217, 1.0, v217
	v_add_f32_e32 v218, 1.0, v218
	v_add_f32_e32 v219, 1.0, v219
	v_rcp_f32_e32 v216, v216
	v_rcp_f32_e32 v217, v217
	v_rcp_f32_e32 v218, v218
	v_rcp_f32_e32 v219, v219
	v_fma_f32 v216, v216, v13, v14
	v_fma_f32 v217, v217, v13, v14
	v_fma_f32 v218, v218, v13, v14
	v_fma_f32 v219, v219, v13, v14
	v_cndmask_b32_e64 v216, v216, v212, s[42:43]
	v_cndmask_b32_e64 v217, v217, v213, s[42:43]
	v_cndmask_b32_e64 v218, v218, v214, s[42:43]
	v_cndmask_b32_e64 v219, v219, v215, s[42:43]
	v_cvt_pk_bf16_f32 v226, v216, v217
	v_cvt_pk_bf16_f32 v227, v218, v219
	v_ashrrev_i32_e32 v225, 31, v224
	v_lshlrev_b64 v[222:223], 9, v[224:225]
	v_lshl_add_u64 v[222:223], v[8:9], 0, v[222:223]
	global_store_dwordx2 v[222:223], v[226:227], off
	s_waitcnt vmcnt(34)
	v_add_u32_e32 v224, s33, v224
	v_and_b32_e32 v210, 0x7ff, v224
	v_cmp_ne_u32_e32 vcc, 0, v210
	v_lshlrev_b32_e32 v212, 16, v104
	v_and_b32_e32 v213, 0xffff0000, v104
	v_lshlrev_b32_e32 v214, 16, v105
	v_and_b32_e32 v215, 0xffff0000, v105
	v_cndmask_b32_e32 v136, 0, v136, vcc
	v_cndmask_b32_e32 v137, 0, v137, vcc
	v_lshlrev_b32_e32 v216, 16, v136
	v_and_b32_e32 v217, 0xffff0000, v136
	v_lshlrev_b32_e32 v218, 16, v137
	v_and_b32_e32 v219, 0xffff0000, v137
	v_sub_f32_e32 v216, v216, v212
	v_sub_f32_e32 v217, v217, v213
	v_sub_f32_e32 v218, v218, v214
	v_sub_f32_e32 v219, v219, v215
	v_fmac_f32_e32 v212, v2, v216
	v_fmac_f32_e32 v213, v3, v217
	v_fmac_f32_e32 v214, v4, v218
	v_fmac_f32_e32 v215, v5, v219
	v_mul_f32_e32 v216, v12, v212
	v_mul_f32_e32 v217, v12, v213
	v_mul_f32_e32 v218, v12, v214
	v_mul_f32_e32 v219, v12, v215
	v_exp_f32_e32 v216, v216
	v_exp_f32_e32 v217, v217
	v_exp_f32_e32 v218, v218
	v_exp_f32_e32 v219, v219
	v_add_f32_e32 v216, 1.0, v216
	v_add_f32_e32 v217, 1.0, v217
	v_add_f32_e32 v218, 1.0, v218
	v_add_f32_e32 v219, 1.0, v219
	v_rcp_f32_e32 v216, v216
	v_rcp_f32_e32 v217, v217
	v_rcp_f32_e32 v218, v218
	v_rcp_f32_e32 v219, v219
	v_fma_f32 v216, v216, v13, v14
	v_fma_f32 v217, v217, v13, v14
	v_fma_f32 v218, v218, v13, v14
	v_fma_f32 v219, v219, v13, v14
	v_cndmask_b32_e64 v216, v216, v212, s[42:43]
	v_cndmask_b32_e64 v217, v217, v213, s[42:43]
	v_cndmask_b32_e64 v218, v218, v214, s[42:43]
	v_cndmask_b32_e64 v219, v219, v215, s[42:43]
	v_cvt_pk_bf16_f32 v220, v216, v217
	v_cvt_pk_bf16_f32 v221, v218, v219
	v_ashrrev_i32_e32 v225, 31, v224
	v_lshlrev_b64 v[222:223], 9, v[224:225]
	v_lshl_add_u64 v[222:223], v[8:9], 0, v[222:223]
	global_store_dwordx2 v[222:223], v[220:221], off
	s_waitcnt vmcnt(33)
	v_add_u32_e32 v224, s33, v224
	v_and_b32_e32 v210, 0x7ff, v224
	v_cmp_ne_u32_e32 vcc, 0, v210
	v_lshlrev_b32_e32 v212, 16, v106
	v_and_b32_e32 v213, 0xffff0000, v106
	v_lshlrev_b32_e32 v214, 16, v107
	v_and_b32_e32 v215, 0xffff0000, v107
	v_cndmask_b32_e32 v138, 0, v138, vcc
	v_cndmask_b32_e32 v139, 0, v139, vcc
	v_lshlrev_b32_e32 v216, 16, v138
	v_and_b32_e32 v217, 0xffff0000, v138
	v_lshlrev_b32_e32 v218, 16, v139
	v_and_b32_e32 v219, 0xffff0000, v139
	v_sub_f32_e32 v216, v216, v212
	v_sub_f32_e32 v217, v217, v213
	v_sub_f32_e32 v218, v218, v214
	v_sub_f32_e32 v219, v219, v215
	v_fmac_f32_e32 v212, v2, v216
	v_fmac_f32_e32 v213, v3, v217
	v_fmac_f32_e32 v214, v4, v218
	v_fmac_f32_e32 v215, v5, v219
	v_mul_f32_e32 v216, v12, v212
	v_mul_f32_e32 v217, v12, v213
	v_mul_f32_e32 v218, v12, v214
	v_mul_f32_e32 v219, v12, v215
	v_exp_f32_e32 v216, v216
	v_exp_f32_e32 v217, v217
	v_exp_f32_e32 v218, v218
	v_exp_f32_e32 v219, v219
	v_add_f32_e32 v216, 1.0, v216
	v_add_f32_e32 v217, 1.0, v217
	v_add_f32_e32 v218, 1.0, v218
	v_add_f32_e32 v219, 1.0, v219
	v_rcp_f32_e32 v216, v216
	v_rcp_f32_e32 v217, v217
	v_rcp_f32_e32 v218, v218
	v_rcp_f32_e32 v219, v219
	v_fma_f32 v216, v216, v13, v14
	v_fma_f32 v217, v217, v13, v14
	v_fma_f32 v218, v218, v13, v14
	v_fma_f32 v219, v219, v13, v14
	v_cndmask_b32_e64 v216, v216, v212, s[42:43]
	v_cndmask_b32_e64 v217, v217, v213, s[42:43]
	v_cndmask_b32_e64 v218, v218, v214, s[42:43]
	v_cndmask_b32_e64 v219, v219, v215, s[42:43]
	v_cvt_pk_bf16_f32 v226, v216, v217
	v_cvt_pk_bf16_f32 v227, v218, v219
	v_ashrrev_i32_e32 v225, 31, v224
	v_lshlrev_b64 v[222:223], 9, v[224:225]
	v_lshl_add_u64 v[222:223], v[8:9], 0, v[222:223]
	global_store_dwordx2 v[222:223], v[226:227], off
	s_waitcnt vmcnt(32)
	v_add_u32_e32 v224, s33, v224
	v_and_b32_e32 v210, 0x7ff, v224
	v_cmp_ne_u32_e32 vcc, 0, v210
	v_lshlrev_b32_e32 v212, 16, v108
	v_and_b32_e32 v213, 0xffff0000, v108
	v_lshlrev_b32_e32 v214, 16, v109
	v_and_b32_e32 v215, 0xffff0000, v109
	v_cndmask_b32_e32 v140, 0, v140, vcc
	v_cndmask_b32_e32 v141, 0, v141, vcc
	v_lshlrev_b32_e32 v216, 16, v140
	v_and_b32_e32 v217, 0xffff0000, v140
	v_lshlrev_b32_e32 v218, 16, v141
	v_and_b32_e32 v219, 0xffff0000, v141
	v_sub_f32_e32 v216, v216, v212
	v_sub_f32_e32 v217, v217, v213
	v_sub_f32_e32 v218, v218, v214
	v_sub_f32_e32 v219, v219, v215
	v_fmac_f32_e32 v212, v2, v216
	v_fmac_f32_e32 v213, v3, v217
	v_fmac_f32_e32 v214, v4, v218
	v_fmac_f32_e32 v215, v5, v219
	v_mul_f32_e32 v216, v12, v212
	v_mul_f32_e32 v217, v12, v213
	v_mul_f32_e32 v218, v12, v214
	v_mul_f32_e32 v219, v12, v215
	v_exp_f32_e32 v216, v216
	v_exp_f32_e32 v217, v217
	v_exp_f32_e32 v218, v218
	v_exp_f32_e32 v219, v219
	v_add_f32_e32 v216, 1.0, v216
	v_add_f32_e32 v217, 1.0, v217
	v_add_f32_e32 v218, 1.0, v218
	v_add_f32_e32 v219, 1.0, v219
	v_rcp_f32_e32 v216, v216
	v_rcp_f32_e32 v217, v217
	v_rcp_f32_e32 v218, v218
	v_rcp_f32_e32 v219, v219
	v_fma_f32 v216, v216, v13, v14
	v_fma_f32 v217, v217, v13, v14
	v_fma_f32 v218, v218, v13, v14
	v_fma_f32 v219, v219, v13, v14
	v_cndmask_b32_e64 v216, v216, v212, s[42:43]
	v_cndmask_b32_e64 v217, v217, v213, s[42:43]
	v_cndmask_b32_e64 v218, v218, v214, s[42:43]
	v_cndmask_b32_e64 v219, v219, v215, s[42:43]
	v_cvt_pk_bf16_f32 v220, v216, v217
	v_cvt_pk_bf16_f32 v221, v218, v219
	v_ashrrev_i32_e32 v225, 31, v224
	v_lshlrev_b64 v[222:223], 9, v[224:225]
	v_lshl_add_u64 v[222:223], v[8:9], 0, v[222:223]
	global_store_dwordx2 v[222:223], v[220:221], off
	s_waitcnt vmcnt(31)
	v_add_u32_e32 v224, s33, v224
	v_and_b32_e32 v210, 0x7ff, v224
	v_cmp_ne_u32_e32 vcc, 0, v210
	v_lshlrev_b32_e32 v212, 16, v110
	v_and_b32_e32 v213, 0xffff0000, v110
	v_lshlrev_b32_e32 v214, 16, v111
	v_and_b32_e32 v215, 0xffff0000, v111
	v_cndmask_b32_e32 v142, 0, v142, vcc
	v_cndmask_b32_e32 v143, 0, v143, vcc
	v_lshlrev_b32_e32 v216, 16, v142
	v_and_b32_e32 v217, 0xffff0000, v142
	v_lshlrev_b32_e32 v218, 16, v143
	v_and_b32_e32 v219, 0xffff0000, v143
	v_sub_f32_e32 v216, v216, v212
	v_sub_f32_e32 v217, v217, v213
	v_sub_f32_e32 v218, v218, v214
	v_sub_f32_e32 v219, v219, v215
	v_fmac_f32_e32 v212, v2, v216
	v_fmac_f32_e32 v213, v3, v217
	v_fmac_f32_e32 v214, v4, v218
	v_fmac_f32_e32 v215, v5, v219
	v_mul_f32_e32 v216, v12, v212
	v_mul_f32_e32 v217, v12, v213
	v_mul_f32_e32 v218, v12, v214
	v_mul_f32_e32 v219, v12, v215
	v_exp_f32_e32 v216, v216
	v_exp_f32_e32 v217, v217
	v_exp_f32_e32 v218, v218
	v_exp_f32_e32 v219, v219
	v_add_f32_e32 v216, 1.0, v216
	v_add_f32_e32 v217, 1.0, v217
	v_add_f32_e32 v218, 1.0, v218
	v_add_f32_e32 v219, 1.0, v219
	v_rcp_f32_e32 v216, v216
	v_rcp_f32_e32 v217, v217
	v_rcp_f32_e32 v218, v218
	v_rcp_f32_e32 v219, v219
	v_fma_f32 v216, v216, v13, v14
	v_fma_f32 v217, v217, v13, v14
	v_fma_f32 v218, v218, v13, v14
	v_fma_f32 v219, v219, v13, v14
	v_cndmask_b32_e64 v216, v216, v212, s[42:43]
	v_cndmask_b32_e64 v217, v217, v213, s[42:43]
	v_cndmask_b32_e64 v218, v218, v214, s[42:43]
	v_cndmask_b32_e64 v219, v219, v215, s[42:43]
	v_cvt_pk_bf16_f32 v226, v216, v217
	v_cvt_pk_bf16_f32 v227, v218, v219
	v_ashrrev_i32_e32 v225, 31, v224
	v_lshlrev_b64 v[222:223], 9, v[224:225]
	v_lshl_add_u64 v[222:223], v[8:9], 0, v[222:223]
	global_store_dwordx2 v[222:223], v[226:227], off
	s_waitcnt vmcnt(0)
